# RWKV scan: capture mask by 64-bit shift, scan waves return from the chunk barrier directly to the scan
# speedup vs baseline: 1.0144x; 1.0144x over previous
.Lrw_fast:
	s_setprio 3
	s_and_b32 s89, s64, 1
	s_mul_i32 s89, s89, 0xc000
	v_lshl_add_u32 v112, s28, 5, v81
	v_lshl_add_u32 v124, v84, 2, s89
	v_lshl_add_u32 v135, v112, 2, s89
	ds_read_b128 v[76:79], v124 offset:272
	ds_read_b128 v[72:75], v124 offset:256
	ds_read_b128 v[68:71], v124 offset:512
	ds_read_b128 v[56:59], v124 offset:528
	ds_read_b32 v0, v135 offset:1280
	ds_read_b128 v[64:67], v124 offset:768
	ds_read_b128 v[60:63], v124 offset:784
	ds_read_b128 v[48:51], v124 offset:0
	ds_read_b128 v[40:43], v124 offset:16
	ds_read_b128 v[52:55], v124 offset:1040
	ds_read_b128 v[44:47], v124 offset:1024
	ds_read_b128 v[156:159], v124 offset:1808
	ds_read_b128 v[152:155], v124 offset:1792
	ds_read_b128 v[182:185], v124 offset:2048
	ds_read_b128 v[186:189], v124 offset:2064
	ds_read_b32 v160, v135 offset:2816
	ds_read_b128 v[190:193], v124 offset:2304
	ds_read_b128 v[194:197], v124 offset:2320
	ds_read_b128 v[144:147], v124 offset:1536
	ds_read_b128 v[148:151], v124 offset:1552
	ds_read_b128 v[202:205], v124 offset:2576
	ds_read_b128 v[198:201], v124 offset:2560
	s_waitcnt lgkmcnt(11)
	v_pk_mul_f32 v[76:77], v[32:33], v[76:77]
	v_pk_mul_f32 v[78:79], v[34:35], v[78:79]
	v_pk_fma_f32 v[72:73], v[36:37], v[72:73], v[76:77]
	v_pk_fma_f32 v[74:75], v[38:39], v[74:75], v[78:79]
	v_pk_add_f32 v[72:73], v[72:73], v[74:75]
	v_add_f32_e32 v142, v72, v73
	s_nop 1
	v_add_f32_dpp v142, v142, v142 quad_perm:[1,0,3,2] row_mask:0xf bank_mask:0xf bound_ctrl:1
	s_nop 1
	v_add_f32_dpp v142, v142, v142 quad_perm:[2,3,0,1] row_mask:0xf bank_mask:0xf bound_ctrl:1
	s_nop 1
	v_add_f32_dpp v142, v142, v142 row_half_mirror row_mask:0xf bank_mask:0xf bound_ctrl:1
	v_pk_mul_f32 v[68:69], v[68:69], v[142:143] op_sel_hi:[1,0]
	v_pk_mul_f32 v[70:71], v[70:71], v[142:143] op_sel_hi:[1,0]
	v_pk_mul_f32 v[56:57], v[56:57], v[142:143] op_sel_hi:[1,0]
	v_pk_mul_f32 v[58:59], v[58:59], v[142:143] op_sel_hi:[1,0]
	v_pk_fma_f32 v[64:65], v[64:65], v[0:1], v[68:69] op_sel_hi:[1,0,1] neg_lo:[0,0,1] neg_hi:[0,0,1]
	v_pk_fma_f32 v[66:67], v[66:67], v[0:1], v[70:71] op_sel_hi:[1,0,1] neg_lo:[0,0,1] neg_hi:[0,0,1]
	v_pk_fma_f32 v[60:61], v[60:61], v[0:1], v[56:57] op_sel_hi:[1,0,1] neg_lo:[0,0,1] neg_hi:[0,0,1]
	v_pk_fma_f32 v[62:63], v[62:63], v[0:1], v[58:59] op_sel_hi:[1,0,1] neg_lo:[0,0,1] neg_hi:[0,0,1]
	v_pk_fma_f32 v[36:37], v[36:37], v[48:49], v[64:65]
	v_pk_fma_f32 v[38:39], v[38:39], v[50:51], v[66:67]
	v_pk_fma_f32 v[32:33], v[32:33], v[40:41], v[60:61]
	v_pk_fma_f32 v[34:35], v[34:35], v[42:43], v[62:63]
	s_waitcnt lgkmcnt(2)
	v_pk_mul_f32 v[156:157], v[32:33], v[156:157]
	v_pk_mul_f32 v[52:53], v[32:33], v[52:53]
	v_pk_mul_f32 v[158:159], v[34:35], v[158:159]
	v_pk_mul_f32 v[54:55], v[34:35], v[54:55]
	v_pk_fma_f32 v[152:153], v[36:37], v[152:153], v[156:157]
	v_pk_fma_f32 v[44:45], v[36:37], v[44:45], v[52:53]
	v_pk_fma_f32 v[154:155], v[38:39], v[154:155], v[158:159]
	v_pk_fma_f32 v[46:47], v[38:39], v[46:47], v[54:55]
	v_pk_add_f32 v[152:153], v[152:153], v[154:155]
	v_pk_add_f32 v[44:45], v[44:45], v[46:47]
	v_add_f32_e32 v142, v152, v153
	v_add_f32_e32 v143, v44, v45
	ds_read_b128 v[76:79], v124 offset:3344
	v_add_f32_dpp v142, v142, v142 quad_perm:[1,0,3,2] row_mask:0xf bank_mask:0xf bound_ctrl:1
	v_add_f32_dpp v143, v143, v143 quad_perm:[1,0,3,2] row_mask:0xf bank_mask:0xf bound_ctrl:1
	ds_read_b128 v[72:75], v124 offset:3328
	v_add_f32_dpp v142, v142, v142 quad_perm:[2,3,0,1] row_mask:0xf bank_mask:0xf bound_ctrl:1
	v_add_f32_dpp v143, v143, v143 quad_perm:[2,3,0,1] row_mask:0xf bank_mask:0xf bound_ctrl:1
	ds_read_b128 v[68:71], v124 offset:3584
	v_add_f32_dpp v142, v142, v142 row_half_mirror row_mask:0xf bank_mask:0xf bound_ctrl:1
	v_add_f32_dpp v143, v143, v143 row_half_mirror row_mask:0xf bank_mask:0xf bound_ctrl:1
	ds_read_b128 v[56:59], v124 offset:3600
	ds_read_b32 v0, v135 offset:4352
	ds_read_b128 v[64:67], v124 offset:3840
	ds_read_b128 v[60:63], v124 offset:3856
	ds_read_b128 v[48:51], v124 offset:3072
	ds_read_b128 v[40:43], v124 offset:3088
	v_pk_mul_f32 v[182:183], v[182:183], v[142:143] op_sel_hi:[1,0]
	v_pk_mul_f32 v[184:185], v[184:185], v[142:143] op_sel_hi:[1,0]
	s_mov_b32 vcc_lo, 0x1010101
	v_pk_mul_f32 v[186:187], v[186:187], v[142:143] op_sel_hi:[1,0]
	v_pk_mul_f32 v[188:189], v[188:189], v[142:143] op_sel_hi:[1,0]
	s_mov_b32 vcc_hi, 0x1010101
	v_pk_fma_f32 v[190:191], v[190:191], v[160:161], v[182:183] op_sel_hi:[1,0,1] neg_lo:[0,0,1] neg_hi:[0,0,1]
	v_pk_fma_f32 v[192:193], v[192:193], v[160:161], v[184:185] op_sel_hi:[1,0,1] neg_lo:[0,0,1] neg_hi:[0,0,1]
	v_cndmask_b32_e32 v134, v134, v143, vcc
	v_pk_fma_f32 v[194:195], v[194:195], v[160:161], v[186:187] op_sel_hi:[1,0,1] neg_lo:[0,0,1] neg_hi:[0,0,1]
	v_pk_fma_f32 v[196:197], v[196:197], v[160:161], v[188:189] op_sel_hi:[1,0,1] neg_lo:[0,0,1] neg_hi:[0,0,1]
	ds_read_b128 v[52:55], v124 offset:4112
	ds_read_b128 v[44:47], v124 offset:4096
	v_pk_fma_f32 v[36:37], v[36:37], v[144:145], v[190:191]
	v_pk_fma_f32 v[38:39], v[38:39], v[146:147], v[192:193]
	v_pk_fma_f32 v[32:33], v[32:33], v[148:149], v[194:195]
	v_pk_fma_f32 v[34:35], v[34:35], v[150:151], v[196:197]
	s_waitcnt lgkmcnt(2)
	v_pk_mul_f32 v[76:77], v[32:33], v[76:77]
	v_pk_mul_f32 v[202:203], v[32:33], v[202:203]
	v_pk_mul_f32 v[78:79], v[34:35], v[78:79]
	v_pk_mul_f32 v[204:205], v[34:35], v[204:205]
	v_pk_fma_f32 v[72:73], v[36:37], v[72:73], v[76:77]
	v_pk_fma_f32 v[198:199], v[36:37], v[198:199], v[202:203]
	v_pk_fma_f32 v[74:75], v[38:39], v[74:75], v[78:79]
	v_pk_fma_f32 v[200:201], v[38:39], v[200:201], v[204:205]
	v_pk_add_f32 v[72:73], v[72:73], v[74:75]
	v_pk_add_f32 v[198:199], v[198:199], v[200:201]
	v_add_f32_e32 v142, v72, v73
	v_add_f32_e32 v143, v198, v199
	ds_read_b128 v[156:159], v124 offset:4880
	v_add_f32_dpp v142, v142, v142 quad_perm:[1,0,3,2] row_mask:0xf bank_mask:0xf bound_ctrl:1
	v_add_f32_dpp v143, v143, v143 quad_perm:[1,0,3,2] row_mask:0xf bank_mask:0xf bound_ctrl:1
	ds_read_b128 v[152:155], v124 offset:4864
	v_add_f32_dpp v142, v142, v142 quad_perm:[2,3,0,1] row_mask:0xf bank_mask:0xf bound_ctrl:1
	v_add_f32_dpp v143, v143, v143 quad_perm:[2,3,0,1] row_mask:0xf bank_mask:0xf bound_ctrl:1
	ds_read_b128 v[182:185], v124 offset:5120
	v_add_f32_dpp v142, v142, v142 row_half_mirror row_mask:0xf bank_mask:0xf bound_ctrl:1
	v_add_f32_dpp v143, v143, v143 row_half_mirror row_mask:0xf bank_mask:0xf bound_ctrl:1
	ds_read_b128 v[186:189], v124 offset:5136
	ds_read_b32 v160, v135 offset:5888
	ds_read_b128 v[190:193], v124 offset:5376
	ds_read_b128 v[194:197], v124 offset:5392
	ds_read_b128 v[144:147], v124 offset:4608
	ds_read_b128 v[148:151], v124 offset:4624
	v_pk_mul_f32 v[68:69], v[68:69], v[142:143] op_sel_hi:[1,0]
	v_pk_mul_f32 v[70:71], v[70:71], v[142:143] op_sel_hi:[1,0]
	s_lshl_b64 vcc, vcc, 1
	v_pk_mul_f32 v[56:57], v[56:57], v[142:143] op_sel_hi:[1,0]
	v_pk_mul_f32 v[58:59], v[58:59], v[142:143] op_sel_hi:[1,0]
	v_pk_fma_f32 v[64:65], v[64:65], v[0:1], v[68:69] op_sel_hi:[1,0,1] neg_lo:[0,0,1] neg_hi:[0,0,1]
	v_pk_fma_f32 v[66:67], v[66:67], v[0:1], v[70:71] op_sel_hi:[1,0,1] neg_lo:[0,0,1] neg_hi:[0,0,1]
	v_cndmask_b32_e32 v134, v134, v143, vcc
	v_pk_fma_f32 v[60:61], v[60:61], v[0:1], v[56:57] op_sel_hi:[1,0,1] neg_lo:[0,0,1] neg_hi:[0,0,1]
	v_pk_fma_f32 v[62:63], v[62:63], v[0:1], v[58:59] op_sel_hi:[1,0,1] neg_lo:[0,0,1] neg_hi:[0,0,1]
	ds_read_b128 v[202:205], v124 offset:5648
	ds_read_b128 v[198:201], v124 offset:5632
	v_pk_fma_f32 v[36:37], v[36:37], v[48:49], v[64:65]
	v_pk_fma_f32 v[38:39], v[38:39], v[50:51], v[66:67]
	v_pk_fma_f32 v[32:33], v[32:33], v[40:41], v[60:61]
	v_pk_fma_f32 v[34:35], v[34:35], v[42:43], v[62:63]
	s_waitcnt lgkmcnt(2)
	v_pk_mul_f32 v[156:157], v[32:33], v[156:157]
	v_pk_mul_f32 v[52:53], v[32:33], v[52:53]
	v_pk_mul_f32 v[158:159], v[34:35], v[158:159]
	v_pk_mul_f32 v[54:55], v[34:35], v[54:55]
	v_pk_fma_f32 v[152:153], v[36:37], v[152:153], v[156:157]
	v_pk_fma_f32 v[44:45], v[36:37], v[44:45], v[52:53]
	v_pk_fma_f32 v[154:155], v[38:39], v[154:155], v[158:159]
	v_pk_fma_f32 v[46:47], v[38:39], v[46:47], v[54:55]
	v_pk_add_f32 v[152:153], v[152:153], v[154:155]
	v_pk_add_f32 v[44:45], v[44:45], v[46:47]
	v_add_f32_e32 v142, v152, v153
	v_add_f32_e32 v143, v44, v45
	ds_read_b128 v[76:79], v124 offset:6416
	v_add_f32_dpp v142, v142, v142 quad_perm:[1,0,3,2] row_mask:0xf bank_mask:0xf bound_ctrl:1
	v_add_f32_dpp v143, v143, v143 quad_perm:[1,0,3,2] row_mask:0xf bank_mask:0xf bound_ctrl:1
	ds_read_b128 v[72:75], v124 offset:6400
	v_add_f32_dpp v142, v142, v142 quad_perm:[2,3,0,1] row_mask:0xf bank_mask:0xf bound_ctrl:1
	v_add_f32_dpp v143, v143, v143 quad_perm:[2,3,0,1] row_mask:0xf bank_mask:0xf bound_ctrl:1
	ds_read_b128 v[68:71], v124 offset:6656
	v_add_f32_dpp v142, v142, v142 row_half_mirror row_mask:0xf bank_mask:0xf bound_ctrl:1
	v_add_f32_dpp v143, v143, v143 row_half_mirror row_mask:0xf bank_mask:0xf bound_ctrl:1
	ds_read_b128 v[56:59], v124 offset:6672
	ds_read_b32 v0, v135 offset:7424
	ds_read_b128 v[64:67], v124 offset:6912
	ds_read_b128 v[60:63], v124 offset:6928
	ds_read_b128 v[48:51], v124 offset:6144
	ds_read_b128 v[40:43], v124 offset:6160
	v_pk_mul_f32 v[182:183], v[182:183], v[142:143] op_sel_hi:[1,0]
	v_pk_mul_f32 v[184:185], v[184:185], v[142:143] op_sel_hi:[1,0]
	s_lshl_b64 vcc, vcc, 1
	v_pk_mul_f32 v[186:187], v[186:187], v[142:143] op_sel_hi:[1,0]
	v_pk_mul_f32 v[188:189], v[188:189], v[142:143] op_sel_hi:[1,0]
	v_pk_fma_f32 v[190:191], v[190:191], v[160:161], v[182:183] op_sel_hi:[1,0,1] neg_lo:[0,0,1] neg_hi:[0,0,1]
	v_pk_fma_f32 v[192:193], v[192:193], v[160:161], v[184:185] op_sel_hi:[1,0,1] neg_lo:[0,0,1] neg_hi:[0,0,1]
	v_cndmask_b32_e32 v134, v134, v143, vcc
	v_pk_fma_f32 v[194:195], v[194:195], v[160:161], v[186:187] op_sel_hi:[1,0,1] neg_lo:[0,0,1] neg_hi:[0,0,1]
	v_pk_fma_f32 v[196:197], v[196:197], v[160:161], v[188:189] op_sel_hi:[1,0,1] neg_lo:[0,0,1] neg_hi:[0,0,1]
	ds_read_b128 v[52:55], v124 offset:7184
	ds_read_b128 v[44:47], v124 offset:7168
	v_pk_fma_f32 v[36:37], v[36:37], v[144:145], v[190:191]
	v_pk_fma_f32 v[38:39], v[38:39], v[146:147], v[192:193]
	v_pk_fma_f32 v[32:33], v[32:33], v[148:149], v[194:195]
	v_pk_fma_f32 v[34:35], v[34:35], v[150:151], v[196:197]
	s_waitcnt lgkmcnt(2)
	v_pk_mul_f32 v[76:77], v[32:33], v[76:77]
	v_pk_mul_f32 v[202:203], v[32:33], v[202:203]
	v_pk_mul_f32 v[78:79], v[34:35], v[78:79]
	v_pk_mul_f32 v[204:205], v[34:35], v[204:205]
	v_pk_fma_f32 v[72:73], v[36:37], v[72:73], v[76:77]
	v_pk_fma_f32 v[198:199], v[36:37], v[198:199], v[202:203]
	v_pk_fma_f32 v[74:75], v[38:39], v[74:75], v[78:79]
	v_pk_fma_f32 v[200:201], v[38:39], v[200:201], v[204:205]
	v_pk_add_f32 v[72:73], v[72:73], v[74:75]
	v_pk_add_f32 v[198:199], v[198:199], v[200:201]
	v_add_f32_e32 v142, v72, v73
	v_add_f32_e32 v143, v198, v199
	ds_read_b128 v[156:159], v124 offset:7952
	v_add_f32_dpp v142, v142, v142 quad_perm:[1,0,3,2] row_mask:0xf bank_mask:0xf bound_ctrl:1
	v_add_f32_dpp v143, v143, v143 quad_perm:[1,0,3,2] row_mask:0xf bank_mask:0xf bound_ctrl:1
	ds_read_b128 v[152:155], v124 offset:7936
	v_add_f32_dpp v142, v142, v142 quad_perm:[2,3,0,1] row_mask:0xf bank_mask:0xf bound_ctrl:1
	v_add_f32_dpp v143, v143, v143 quad_perm:[2,3,0,1] row_mask:0xf bank_mask:0xf bound_ctrl:1
	ds_read_b128 v[182:185], v124 offset:8192
	v_add_f32_dpp v142, v142, v142 row_half_mirror row_mask:0xf bank_mask:0xf bound_ctrl:1
	v_add_f32_dpp v143, v143, v143 row_half_mirror row_mask:0xf bank_mask:0xf bound_ctrl:1
	ds_read_b128 v[186:189], v124 offset:8208
	ds_read_b32 v160, v135 offset:8960
	ds_read_b128 v[190:193], v124 offset:8448
	ds_read_b128 v[194:197], v124 offset:8464
	ds_read_b128 v[144:147], v124 offset:7680
	ds_read_b128 v[148:151], v124 offset:7696
	v_pk_mul_f32 v[68:69], v[68:69], v[142:143] op_sel_hi:[1,0]
	v_pk_mul_f32 v[70:71], v[70:71], v[142:143] op_sel_hi:[1,0]
	s_lshl_b64 vcc, vcc, 1
	v_pk_mul_f32 v[56:57], v[56:57], v[142:143] op_sel_hi:[1,0]
	v_pk_mul_f32 v[58:59], v[58:59], v[142:143] op_sel_hi:[1,0]
	v_pk_fma_f32 v[64:65], v[64:65], v[0:1], v[68:69] op_sel_hi:[1,0,1] neg_lo:[0,0,1] neg_hi:[0,0,1]
	v_pk_fma_f32 v[66:67], v[66:67], v[0:1], v[70:71] op_sel_hi:[1,0,1] neg_lo:[0,0,1] neg_hi:[0,0,1]
	v_cndmask_b32_e32 v134, v134, v143, vcc
	v_pk_fma_f32 v[60:61], v[60:61], v[0:1], v[56:57] op_sel_hi:[1,0,1] neg_lo:[0,0,1] neg_hi:[0,0,1]
	v_pk_fma_f32 v[62:63], v[62:63], v[0:1], v[58:59] op_sel_hi:[1,0,1] neg_lo:[0,0,1] neg_hi:[0,0,1]
	ds_read_b128 v[202:205], v124 offset:8720
	ds_read_b128 v[198:201], v124 offset:8704
	v_pk_fma_f32 v[36:37], v[36:37], v[48:49], v[64:65]
	v_pk_fma_f32 v[38:39], v[38:39], v[50:51], v[66:67]
	v_pk_fma_f32 v[32:33], v[32:33], v[40:41], v[60:61]
	v_pk_fma_f32 v[34:35], v[34:35], v[42:43], v[62:63]
	s_waitcnt lgkmcnt(2)
	v_pk_mul_f32 v[156:157], v[32:33], v[156:157]
	v_pk_mul_f32 v[52:53], v[32:33], v[52:53]
	v_pk_mul_f32 v[158:159], v[34:35], v[158:159]
	v_pk_mul_f32 v[54:55], v[34:35], v[54:55]
	v_pk_fma_f32 v[152:153], v[36:37], v[152:153], v[156:157]
	v_pk_fma_f32 v[44:45], v[36:37], v[44:45], v[52:53]
	v_pk_fma_f32 v[154:155], v[38:39], v[154:155], v[158:159]
	v_pk_fma_f32 v[46:47], v[38:39], v[46:47], v[54:55]
	v_pk_add_f32 v[152:153], v[152:153], v[154:155]
	v_pk_add_f32 v[44:45], v[44:45], v[46:47]
	v_add_f32_e32 v142, v152, v153
	v_add_f32_e32 v143, v44, v45
	ds_read_b128 v[76:79], v124 offset:9488
	v_add_f32_dpp v142, v142, v142 quad_perm:[1,0,3,2] row_mask:0xf bank_mask:0xf bound_ctrl:1
	v_add_f32_dpp v143, v143, v143 quad_perm:[1,0,3,2] row_mask:0xf bank_mask:0xf bound_ctrl:1
	ds_read_b128 v[72:75], v124 offset:9472
	v_add_f32_dpp v142, v142, v142 quad_perm:[2,3,0,1] row_mask:0xf bank_mask:0xf bound_ctrl:1
	v_add_f32_dpp v143, v143, v143 quad_perm:[2,3,0,1] row_mask:0xf bank_mask:0xf bound_ctrl:1
	ds_read_b128 v[68:71], v124 offset:9728
	v_add_f32_dpp v142, v142, v142 row_half_mirror row_mask:0xf bank_mask:0xf bound_ctrl:1
	v_add_f32_dpp v143, v143, v143 row_half_mirror row_mask:0xf bank_mask:0xf bound_ctrl:1
	ds_read_b128 v[56:59], v124 offset:9744
	ds_read_b32 v0, v135 offset:10496
	ds_read_b128 v[64:67], v124 offset:9984
	ds_read_b128 v[60:63], v124 offset:10000
	ds_read_b128 v[48:51], v124 offset:9216
	ds_read_b128 v[40:43], v124 offset:9232
	v_pk_mul_f32 v[182:183], v[182:183], v[142:143] op_sel_hi:[1,0]
	v_pk_mul_f32 v[184:185], v[184:185], v[142:143] op_sel_hi:[1,0]
	s_lshl_b64 vcc, vcc, 1
	v_pk_mul_f32 v[186:187], v[186:187], v[142:143] op_sel_hi:[1,0]
	v_pk_mul_f32 v[188:189], v[188:189], v[142:143] op_sel_hi:[1,0]
	v_pk_fma_f32 v[190:191], v[190:191], v[160:161], v[182:183] op_sel_hi:[1,0,1] neg_lo:[0,0,1] neg_hi:[0,0,1]
	v_pk_fma_f32 v[192:193], v[192:193], v[160:161], v[184:185] op_sel_hi:[1,0,1] neg_lo:[0,0,1] neg_hi:[0,0,1]
	v_cndmask_b32_e32 v134, v134, v143, vcc
	v_pk_fma_f32 v[194:195], v[194:195], v[160:161], v[186:187] op_sel_hi:[1,0,1] neg_lo:[0,0,1] neg_hi:[0,0,1]
	v_pk_fma_f32 v[196:197], v[196:197], v[160:161], v[188:189] op_sel_hi:[1,0,1] neg_lo:[0,0,1] neg_hi:[0,0,1]
	ds_read_b128 v[52:55], v124 offset:10256
	ds_read_b128 v[44:47], v124 offset:10240
	v_pk_fma_f32 v[36:37], v[36:37], v[144:145], v[190:191]
	v_pk_fma_f32 v[38:39], v[38:39], v[146:147], v[192:193]
	v_pk_fma_f32 v[32:33], v[32:33], v[148:149], v[194:195]
	v_pk_fma_f32 v[34:35], v[34:35], v[150:151], v[196:197]
	s_waitcnt lgkmcnt(2)
	v_pk_mul_f32 v[76:77], v[32:33], v[76:77]
	v_pk_mul_f32 v[202:203], v[32:33], v[202:203]
	v_pk_mul_f32 v[78:79], v[34:35], v[78:79]
	v_pk_mul_f32 v[204:205], v[34:35], v[204:205]
	v_pk_fma_f32 v[72:73], v[36:37], v[72:73], v[76:77]
	v_pk_fma_f32 v[198:199], v[36:37], v[198:199], v[202:203]
	v_pk_fma_f32 v[74:75], v[38:39], v[74:75], v[78:79]
	v_pk_fma_f32 v[200:201], v[38:39], v[200:201], v[204:205]
	v_pk_add_f32 v[72:73], v[72:73], v[74:75]
	v_pk_add_f32 v[198:199], v[198:199], v[200:201]
	v_add_f32_e32 v142, v72, v73
	v_add_f32_e32 v143, v198, v199
	ds_read_b128 v[156:159], v124 offset:11024
	v_add_f32_dpp v142, v142, v142 quad_perm:[1,0,3,2] row_mask:0xf bank_mask:0xf bound_ctrl:1
	v_add_f32_dpp v143, v143, v143 quad_perm:[1,0,3,2] row_mask:0xf bank_mask:0xf bound_ctrl:1
	ds_read_b128 v[152:155], v124 offset:11008
	v_add_f32_dpp v142, v142, v142 quad_perm:[2,3,0,1] row_mask:0xf bank_mask:0xf bound_ctrl:1
	v_add_f32_dpp v143, v143, v143 quad_perm:[2,3,0,1] row_mask:0xf bank_mask:0xf bound_ctrl:1
	ds_read_b128 v[182:185], v124 offset:11264
	v_add_f32_dpp v142, v142, v142 row_half_mirror row_mask:0xf bank_mask:0xf bound_ctrl:1
	v_add_f32_dpp v143, v143, v143 row_half_mirror row_mask:0xf bank_mask:0xf bound_ctrl:1
	ds_read_b128 v[186:189], v124 offset:11280
	ds_read_b32 v160, v135 offset:12032
	ds_read_b128 v[190:193], v124 offset:11520
	ds_read_b128 v[194:197], v124 offset:11536
	ds_read_b128 v[144:147], v124 offset:10752
	ds_read_b128 v[148:151], v124 offset:10768
	v_pk_mul_f32 v[68:69], v[68:69], v[142:143] op_sel_hi:[1,0]
	v_pk_mul_f32 v[70:71], v[70:71], v[142:143] op_sel_hi:[1,0]
	s_lshl_b64 vcc, vcc, 1
	v_pk_mul_f32 v[56:57], v[56:57], v[142:143] op_sel_hi:[1,0]
	v_pk_mul_f32 v[58:59], v[58:59], v[142:143] op_sel_hi:[1,0]
	v_pk_fma_f32 v[64:65], v[64:65], v[0:1], v[68:69] op_sel_hi:[1,0,1] neg_lo:[0,0,1] neg_hi:[0,0,1]
	v_pk_fma_f32 v[66:67], v[66:67], v[0:1], v[70:71] op_sel_hi:[1,0,1] neg_lo:[0,0,1] neg_hi:[0,0,1]
	v_cndmask_b32_e32 v134, v134, v143, vcc
	v_pk_fma_f32 v[60:61], v[60:61], v[0:1], v[56:57] op_sel_hi:[1,0,1] neg_lo:[0,0,1] neg_hi:[0,0,1]
	v_pk_fma_f32 v[62:63], v[62:63], v[0:1], v[58:59] op_sel_hi:[1,0,1] neg_lo:[0,0,1] neg_hi:[0,0,1]
	ds_read_b128 v[202:205], v124 offset:11792
	ds_read_b128 v[198:201], v124 offset:11776
	v_pk_fma_f32 v[36:37], v[36:37], v[48:49], v[64:65]
	v_pk_fma_f32 v[38:39], v[38:39], v[50:51], v[66:67]
	v_pk_fma_f32 v[32:33], v[32:33], v[40:41], v[60:61]
	v_pk_fma_f32 v[34:35], v[34:35], v[42:43], v[62:63]
	s_waitcnt lgkmcnt(2)
	v_pk_mul_f32 v[156:157], v[32:33], v[156:157]
	v_pk_mul_f32 v[52:53], v[32:33], v[52:53]
	v_pk_mul_f32 v[158:159], v[34:35], v[158:159]
	v_pk_mul_f32 v[54:55], v[34:35], v[54:55]
	v_pk_fma_f32 v[152:153], v[36:37], v[152:153], v[156:157]
	v_pk_fma_f32 v[44:45], v[36:37], v[44:45], v[52:53]
	v_pk_fma_f32 v[154:155], v[38:39], v[154:155], v[158:159]
	v_pk_fma_f32 v[46:47], v[38:39], v[46:47], v[54:55]
	v_pk_add_f32 v[152:153], v[152:153], v[154:155]
	v_pk_add_f32 v[44:45], v[44:45], v[46:47]
	v_add_f32_e32 v142, v152, v153
	v_add_f32_e32 v143, v44, v45
	ds_read_b128 v[76:79], v124 offset:12560
	v_add_f32_dpp v142, v142, v142 quad_perm:[1,0,3,2] row_mask:0xf bank_mask:0xf bound_ctrl:1
	v_add_f32_dpp v143, v143, v143 quad_perm:[1,0,3,2] row_mask:0xf bank_mask:0xf bound_ctrl:1
	ds_read_b128 v[72:75], v124 offset:12544
	v_add_f32_dpp v142, v142, v142 quad_perm:[2,3,0,1] row_mask:0xf bank_mask:0xf bound_ctrl:1
	v_add_f32_dpp v143, v143, v143 quad_perm:[2,3,0,1] row_mask:0xf bank_mask:0xf bound_ctrl:1
	ds_read_b128 v[68:71], v124 offset:12800
	v_add_f32_dpp v142, v142, v142 row_half_mirror row_mask:0xf bank_mask:0xf bound_ctrl:1
	v_add_f32_dpp v143, v143, v143 row_half_mirror row_mask:0xf bank_mask:0xf bound_ctrl:1
	ds_read_b128 v[56:59], v124 offset:12816
	ds_read_b32 v0, v135 offset:13568
	ds_read_b128 v[64:67], v124 offset:13056
	ds_read_b128 v[60:63], v124 offset:13072
	ds_read_b128 v[48:51], v124 offset:12288
	ds_read_b128 v[40:43], v124 offset:12304
	v_pk_mul_f32 v[182:183], v[182:183], v[142:143] op_sel_hi:[1,0]
	v_pk_mul_f32 v[184:185], v[184:185], v[142:143] op_sel_hi:[1,0]
	s_lshl_b64 vcc, vcc, 1
	v_pk_mul_f32 v[186:187], v[186:187], v[142:143] op_sel_hi:[1,0]
	v_pk_mul_f32 v[188:189], v[188:189], v[142:143] op_sel_hi:[1,0]
	v_pk_fma_f32 v[190:191], v[190:191], v[160:161], v[182:183] op_sel_hi:[1,0,1] neg_lo:[0,0,1] neg_hi:[0,0,1]
	v_pk_fma_f32 v[192:193], v[192:193], v[160:161], v[184:185] op_sel_hi:[1,0,1] neg_lo:[0,0,1] neg_hi:[0,0,1]
	v_cndmask_b32_e32 v134, v134, v143, vcc
	v_pk_fma_f32 v[194:195], v[194:195], v[160:161], v[186:187] op_sel_hi:[1,0,1] neg_lo:[0,0,1] neg_hi:[0,0,1]
	v_pk_fma_f32 v[196:197], v[196:197], v[160:161], v[188:189] op_sel_hi:[1,0,1] neg_lo:[0,0,1] neg_hi:[0,0,1]
	ds_read_b128 v[52:55], v124 offset:13328
	ds_read_b128 v[44:47], v124 offset:13312
	v_pk_fma_f32 v[36:37], v[36:37], v[144:145], v[190:191]
	v_pk_fma_f32 v[38:39], v[38:39], v[146:147], v[192:193]
	v_pk_fma_f32 v[32:33], v[32:33], v[148:149], v[194:195]
	v_pk_fma_f32 v[34:35], v[34:35], v[150:151], v[196:197]
	s_waitcnt lgkmcnt(2)
	v_pk_mul_f32 v[76:77], v[32:33], v[76:77]
	v_pk_mul_f32 v[202:203], v[32:33], v[202:203]
	v_pk_mul_f32 v[78:79], v[34:35], v[78:79]
	v_pk_mul_f32 v[204:205], v[34:35], v[204:205]
	v_pk_fma_f32 v[72:73], v[36:37], v[72:73], v[76:77]
	v_pk_fma_f32 v[198:199], v[36:37], v[198:199], v[202:203]
	v_pk_fma_f32 v[74:75], v[38:39], v[74:75], v[78:79]
	v_pk_fma_f32 v[200:201], v[38:39], v[200:201], v[204:205]
	v_pk_add_f32 v[72:73], v[72:73], v[74:75]
	v_pk_add_f32 v[198:199], v[198:199], v[200:201]
	v_add_f32_e32 v142, v72, v73
	v_add_f32_e32 v143, v198, v199
	ds_read_b128 v[156:159], v124 offset:14096
	v_add_f32_dpp v142, v142, v142 quad_perm:[1,0,3,2] row_mask:0xf bank_mask:0xf bound_ctrl:1
	v_add_f32_dpp v143, v143, v143 quad_perm:[1,0,3,2] row_mask:0xf bank_mask:0xf bound_ctrl:1
	ds_read_b128 v[152:155], v124 offset:14080
	v_add_f32_dpp v142, v142, v142 quad_perm:[2,3,0,1] row_mask:0xf bank_mask:0xf bound_ctrl:1
	v_add_f32_dpp v143, v143, v143 quad_perm:[2,3,0,1] row_mask:0xf bank_mask:0xf bound_ctrl:1
	ds_read_b128 v[182:185], v124 offset:14336
	v_add_f32_dpp v142, v142, v142 row_half_mirror row_mask:0xf bank_mask:0xf bound_ctrl:1
	v_add_f32_dpp v143, v143, v143 row_half_mirror row_mask:0xf bank_mask:0xf bound_ctrl:1
	ds_read_b128 v[186:189], v124 offset:14352
	ds_read_b32 v160, v135 offset:15104
	ds_read_b128 v[190:193], v124 offset:14592
	ds_read_b128 v[194:197], v124 offset:14608
	ds_read_b128 v[144:147], v124 offset:13824
	ds_read_b128 v[148:151], v124 offset:13840
	v_pk_mul_f32 v[68:69], v[68:69], v[142:143] op_sel_hi:[1,0]
	v_pk_mul_f32 v[70:71], v[70:71], v[142:143] op_sel_hi:[1,0]
	s_lshl_b64 vcc, vcc, 1
	v_pk_mul_f32 v[56:57], v[56:57], v[142:143] op_sel_hi:[1,0]
	v_pk_mul_f32 v[58:59], v[58:59], v[142:143] op_sel_hi:[1,0]
	v_pk_fma_f32 v[64:65], v[64:65], v[0:1], v[68:69] op_sel_hi:[1,0,1] neg_lo:[0,0,1] neg_hi:[0,0,1]
	v_pk_fma_f32 v[66:67], v[66:67], v[0:1], v[70:71] op_sel_hi:[1,0,1] neg_lo:[0,0,1] neg_hi:[0,0,1]
	v_cndmask_b32_e32 v134, v134, v143, vcc
	v_pk_fma_f32 v[60:61], v[60:61], v[0:1], v[56:57] op_sel_hi:[1,0,1] neg_lo:[0,0,1] neg_hi:[0,0,1]
	v_pk_fma_f32 v[62:63], v[62:63], v[0:1], v[58:59] op_sel_hi:[1,0,1] neg_lo:[0,0,1] neg_hi:[0,0,1]
	ds_read_b128 v[202:205], v124 offset:14864
	ds_read_b128 v[198:201], v124 offset:14848
	v_pk_fma_f32 v[36:37], v[36:37], v[48:49], v[64:65]
	v_pk_fma_f32 v[38:39], v[38:39], v[50:51], v[66:67]
	v_pk_fma_f32 v[32:33], v[32:33], v[40:41], v[60:61]
	v_pk_fma_f32 v[34:35], v[34:35], v[42:43], v[62:63]
	s_waitcnt lgkmcnt(2)
	v_pk_mul_f32 v[156:157], v[32:33], v[156:157]
	v_pk_mul_f32 v[52:53], v[32:33], v[52:53]
	v_pk_mul_f32 v[158:159], v[34:35], v[158:159]
	v_pk_mul_f32 v[54:55], v[34:35], v[54:55]
	v_pk_fma_f32 v[152:153], v[36:37], v[152:153], v[156:157]
	v_pk_fma_f32 v[44:45], v[36:37], v[44:45], v[52:53]
	v_pk_fma_f32 v[154:155], v[38:39], v[154:155], v[158:159]
	v_pk_fma_f32 v[46:47], v[38:39], v[46:47], v[54:55]
	v_pk_add_f32 v[152:153], v[152:153], v[154:155]
	v_pk_add_f32 v[44:45], v[44:45], v[46:47]
	v_add_f32_e32 v142, v152, v153
	v_add_f32_e32 v143, v44, v45
	ds_read_b128 v[76:79], v124 offset:15632
	v_add_f32_dpp v142, v142, v142 quad_perm:[1,0,3,2] row_mask:0xf bank_mask:0xf bound_ctrl:1
	v_add_f32_dpp v143, v143, v143 quad_perm:[1,0,3,2] row_mask:0xf bank_mask:0xf bound_ctrl:1
	ds_read_b128 v[72:75], v124 offset:15616
	v_add_f32_dpp v142, v142, v142 quad_perm:[2,3,0,1] row_mask:0xf bank_mask:0xf bound_ctrl:1
	v_add_f32_dpp v143, v143, v143 quad_perm:[2,3,0,1] row_mask:0xf bank_mask:0xf bound_ctrl:1
	ds_read_b128 v[68:71], v124 offset:15872
	v_add_f32_dpp v142, v142, v142 row_half_mirror row_mask:0xf bank_mask:0xf bound_ctrl:1
	v_add_f32_dpp v143, v143, v143 row_half_mirror row_mask:0xf bank_mask:0xf bound_ctrl:1
	ds_read_b128 v[56:59], v124 offset:15888
	ds_read_b32 v0, v135 offset:16640
	ds_read_b128 v[64:67], v124 offset:16128
	ds_read_b128 v[60:63], v124 offset:16144
	ds_read_b128 v[48:51], v124 offset:15360
	ds_read_b128 v[40:43], v124 offset:15376
	v_pk_mul_f32 v[182:183], v[182:183], v[142:143] op_sel_hi:[1,0]
	v_pk_mul_f32 v[184:185], v[184:185], v[142:143] op_sel_hi:[1,0]
	s_mov_b32 vcc_lo, 0x1010101
	v_pk_mul_f32 v[186:187], v[186:187], v[142:143] op_sel_hi:[1,0]
	v_pk_mul_f32 v[188:189], v[188:189], v[142:143] op_sel_hi:[1,0]
	s_mov_b32 vcc_hi, 0x1010101
	v_pk_fma_f32 v[190:191], v[190:191], v[160:161], v[182:183] op_sel_hi:[1,0,1] neg_lo:[0,0,1] neg_hi:[0,0,1]
	v_pk_fma_f32 v[192:193], v[192:193], v[160:161], v[184:185] op_sel_hi:[1,0,1] neg_lo:[0,0,1] neg_hi:[0,0,1]
	v_cndmask_b32_e32 v133, v133, v143, vcc
	v_pk_fma_f32 v[194:195], v[194:195], v[160:161], v[186:187] op_sel_hi:[1,0,1] neg_lo:[0,0,1] neg_hi:[0,0,1]
	v_pk_fma_f32 v[196:197], v[196:197], v[160:161], v[188:189] op_sel_hi:[1,0,1] neg_lo:[0,0,1] neg_hi:[0,0,1]
	ds_read_b128 v[52:55], v124 offset:16400
	ds_read_b128 v[44:47], v124 offset:16384
	v_pk_fma_f32 v[36:37], v[36:37], v[144:145], v[190:191]
	v_pk_fma_f32 v[38:39], v[38:39], v[146:147], v[192:193]
	v_pk_fma_f32 v[32:33], v[32:33], v[148:149], v[194:195]
	v_pk_fma_f32 v[34:35], v[34:35], v[150:151], v[196:197]
	s_waitcnt lgkmcnt(2)
	v_pk_mul_f32 v[76:77], v[32:33], v[76:77]
	v_pk_mul_f32 v[202:203], v[32:33], v[202:203]
	v_pk_mul_f32 v[78:79], v[34:35], v[78:79]
	v_pk_mul_f32 v[204:205], v[34:35], v[204:205]
	v_pk_fma_f32 v[72:73], v[36:37], v[72:73], v[76:77]
	v_pk_fma_f32 v[198:199], v[36:37], v[198:199], v[202:203]
	v_pk_fma_f32 v[74:75], v[38:39], v[74:75], v[78:79]
	v_pk_fma_f32 v[200:201], v[38:39], v[200:201], v[204:205]
	v_pk_add_f32 v[72:73], v[72:73], v[74:75]
	v_pk_add_f32 v[198:199], v[198:199], v[200:201]
	v_add_f32_e32 v142, v72, v73
	v_add_f32_e32 v143, v198, v199
	ds_read_b128 v[156:159], v124 offset:17168
	v_add_f32_dpp v142, v142, v142 quad_perm:[1,0,3,2] row_mask:0xf bank_mask:0xf bound_ctrl:1
	v_add_f32_dpp v143, v143, v143 quad_perm:[1,0,3,2] row_mask:0xf bank_mask:0xf bound_ctrl:1
	ds_read_b128 v[152:155], v124 offset:17152
	v_add_f32_dpp v142, v142, v142 quad_perm:[2,3,0,1] row_mask:0xf bank_mask:0xf bound_ctrl:1
	v_add_f32_dpp v143, v143, v143 quad_perm:[2,3,0,1] row_mask:0xf bank_mask:0xf bound_ctrl:1
	ds_read_b128 v[182:185], v124 offset:17408
	v_add_f32_dpp v142, v142, v142 row_half_mirror row_mask:0xf bank_mask:0xf bound_ctrl:1
	v_add_f32_dpp v143, v143, v143 row_half_mirror row_mask:0xf bank_mask:0xf bound_ctrl:1
	ds_read_b128 v[186:189], v124 offset:17424
	ds_read_b32 v160, v135 offset:18176
	ds_read_b128 v[190:193], v124 offset:17664
	ds_read_b128 v[194:197], v124 offset:17680
	ds_read_b128 v[144:147], v124 offset:16896
	ds_read_b128 v[148:151], v124 offset:16912
	v_pk_mul_f32 v[68:69], v[68:69], v[142:143] op_sel_hi:[1,0]
	v_pk_mul_f32 v[70:71], v[70:71], v[142:143] op_sel_hi:[1,0]
	s_lshl_b64 vcc, vcc, 1
	v_pk_mul_f32 v[56:57], v[56:57], v[142:143] op_sel_hi:[1,0]
	v_pk_mul_f32 v[58:59], v[58:59], v[142:143] op_sel_hi:[1,0]
	v_pk_fma_f32 v[64:65], v[64:65], v[0:1], v[68:69] op_sel_hi:[1,0,1] neg_lo:[0,0,1] neg_hi:[0,0,1]
	v_pk_fma_f32 v[66:67], v[66:67], v[0:1], v[70:71] op_sel_hi:[1,0,1] neg_lo:[0,0,1] neg_hi:[0,0,1]
	v_cndmask_b32_e32 v133, v133, v143, vcc
	v_pk_fma_f32 v[60:61], v[60:61], v[0:1], v[56:57] op_sel_hi:[1,0,1] neg_lo:[0,0,1] neg_hi:[0,0,1]
	v_pk_fma_f32 v[62:63], v[62:63], v[0:1], v[58:59] op_sel_hi:[1,0,1] neg_lo:[0,0,1] neg_hi:[0,0,1]
	ds_read_b128 v[202:205], v124 offset:17936
	ds_read_b128 v[198:201], v124 offset:17920
	v_pk_fma_f32 v[36:37], v[36:37], v[48:49], v[64:65]
	v_pk_fma_f32 v[38:39], v[38:39], v[50:51], v[66:67]
	v_pk_fma_f32 v[32:33], v[32:33], v[40:41], v[60:61]
	v_pk_fma_f32 v[34:35], v[34:35], v[42:43], v[62:63]
	s_waitcnt lgkmcnt(2)
	v_pk_mul_f32 v[156:157], v[32:33], v[156:157]
	v_pk_mul_f32 v[52:53], v[32:33], v[52:53]
	v_pk_mul_f32 v[158:159], v[34:35], v[158:159]
	v_pk_mul_f32 v[54:55], v[34:35], v[54:55]
	v_pk_fma_f32 v[152:153], v[36:37], v[152:153], v[156:157]
	v_pk_fma_f32 v[44:45], v[36:37], v[44:45], v[52:53]
	v_pk_fma_f32 v[154:155], v[38:39], v[154:155], v[158:159]
	v_pk_fma_f32 v[46:47], v[38:39], v[46:47], v[54:55]
	v_pk_add_f32 v[152:153], v[152:153], v[154:155]
	v_pk_add_f32 v[44:45], v[44:45], v[46:47]
	v_add_f32_e32 v142, v152, v153
	v_add_f32_e32 v143, v44, v45
	ds_read_b128 v[76:79], v124 offset:18704
	v_add_f32_dpp v142, v142, v142 quad_perm:[1,0,3,2] row_mask:0xf bank_mask:0xf bound_ctrl:1
	v_add_f32_dpp v143, v143, v143 quad_perm:[1,0,3,2] row_mask:0xf bank_mask:0xf bound_ctrl:1
	ds_read_b128 v[72:75], v124 offset:18688
	v_add_f32_dpp v142, v142, v142 quad_perm:[2,3,0,1] row_mask:0xf bank_mask:0xf bound_ctrl:1
	v_add_f32_dpp v143, v143, v143 quad_perm:[2,3,0,1] row_mask:0xf bank_mask:0xf bound_ctrl:1
	ds_read_b128 v[68:71], v124 offset:18944
	v_add_f32_dpp v142, v142, v142 row_half_mirror row_mask:0xf bank_mask:0xf bound_ctrl:1
	v_add_f32_dpp v143, v143, v143 row_half_mirror row_mask:0xf bank_mask:0xf bound_ctrl:1
	ds_read_b128 v[56:59], v124 offset:18960
	ds_read_b32 v0, v135 offset:19712
	ds_read_b128 v[64:67], v124 offset:19200
	ds_read_b128 v[60:63], v124 offset:19216
	ds_read_b128 v[48:51], v124 offset:18432
	ds_read_b128 v[40:43], v124 offset:18448
	v_pk_mul_f32 v[182:183], v[182:183], v[142:143] op_sel_hi:[1,0]
	v_pk_mul_f32 v[184:185], v[184:185], v[142:143] op_sel_hi:[1,0]
	s_lshl_b64 vcc, vcc, 1
	v_pk_mul_f32 v[186:187], v[186:187], v[142:143] op_sel_hi:[1,0]
	v_pk_mul_f32 v[188:189], v[188:189], v[142:143] op_sel_hi:[1,0]
	v_pk_fma_f32 v[190:191], v[190:191], v[160:161], v[182:183] op_sel_hi:[1,0,1] neg_lo:[0,0,1] neg_hi:[0,0,1]
	v_pk_fma_f32 v[192:193], v[192:193], v[160:161], v[184:185] op_sel_hi:[1,0,1] neg_lo:[0,0,1] neg_hi:[0,0,1]
	v_cndmask_b32_e32 v133, v133, v143, vcc
	v_pk_fma_f32 v[194:195], v[194:195], v[160:161], v[186:187] op_sel_hi:[1,0,1] neg_lo:[0,0,1] neg_hi:[0,0,1]
	v_pk_fma_f32 v[196:197], v[196:197], v[160:161], v[188:189] op_sel_hi:[1,0,1] neg_lo:[0,0,1] neg_hi:[0,0,1]
	ds_read_b128 v[52:55], v124 offset:19472
	ds_read_b128 v[44:47], v124 offset:19456
	v_pk_fma_f32 v[36:37], v[36:37], v[144:145], v[190:191]
	v_pk_fma_f32 v[38:39], v[38:39], v[146:147], v[192:193]
	v_pk_fma_f32 v[32:33], v[32:33], v[148:149], v[194:195]
	v_pk_fma_f32 v[34:35], v[34:35], v[150:151], v[196:197]
	s_waitcnt lgkmcnt(2)
	v_pk_mul_f32 v[76:77], v[32:33], v[76:77]
	v_pk_mul_f32 v[202:203], v[32:33], v[202:203]
	v_pk_mul_f32 v[78:79], v[34:35], v[78:79]
	v_pk_mul_f32 v[204:205], v[34:35], v[204:205]
	v_pk_fma_f32 v[72:73], v[36:37], v[72:73], v[76:77]
	v_pk_fma_f32 v[198:199], v[36:37], v[198:199], v[202:203]
	v_pk_fma_f32 v[74:75], v[38:39], v[74:75], v[78:79]
	v_pk_fma_f32 v[200:201], v[38:39], v[200:201], v[204:205]
	v_pk_add_f32 v[72:73], v[72:73], v[74:75]
	v_pk_add_f32 v[198:199], v[198:199], v[200:201]
	v_add_f32_e32 v142, v72, v73
	v_add_f32_e32 v143, v198, v199
	ds_read_b128 v[156:159], v124 offset:20240
	v_add_f32_dpp v142, v142, v142 quad_perm:[1,0,3,2] row_mask:0xf bank_mask:0xf bound_ctrl:1
	v_add_f32_dpp v143, v143, v143 quad_perm:[1,0,3,2] row_mask:0xf bank_mask:0xf bound_ctrl:1
	ds_read_b128 v[152:155], v124 offset:20224
	v_add_f32_dpp v142, v142, v142 quad_perm:[2,3,0,1] row_mask:0xf bank_mask:0xf bound_ctrl:1
	v_add_f32_dpp v143, v143, v143 quad_perm:[2,3,0,1] row_mask:0xf bank_mask:0xf bound_ctrl:1
	ds_read_b128 v[182:185], v124 offset:20480
	v_add_f32_dpp v142, v142, v142 row_half_mirror row_mask:0xf bank_mask:0xf bound_ctrl:1
	v_add_f32_dpp v143, v143, v143 row_half_mirror row_mask:0xf bank_mask:0xf bound_ctrl:1
	ds_read_b128 v[186:189], v124 offset:20496
	ds_read_b32 v160, v135 offset:21248
	ds_read_b128 v[190:193], v124 offset:20736
	ds_read_b128 v[194:197], v124 offset:20752
	ds_read_b128 v[144:147], v124 offset:19968
	ds_read_b128 v[148:151], v124 offset:19984
	v_pk_mul_f32 v[68:69], v[68:69], v[142:143] op_sel_hi:[1,0]
	v_pk_mul_f32 v[70:71], v[70:71], v[142:143] op_sel_hi:[1,0]
	s_lshl_b64 vcc, vcc, 1
	v_pk_mul_f32 v[56:57], v[56:57], v[142:143] op_sel_hi:[1,0]
	v_pk_mul_f32 v[58:59], v[58:59], v[142:143] op_sel_hi:[1,0]
	v_pk_fma_f32 v[64:65], v[64:65], v[0:1], v[68:69] op_sel_hi:[1,0,1] neg_lo:[0,0,1] neg_hi:[0,0,1]
	v_pk_fma_f32 v[66:67], v[66:67], v[0:1], v[70:71] op_sel_hi:[1,0,1] neg_lo:[0,0,1] neg_hi:[0,0,1]
	v_cndmask_b32_e32 v133, v133, v143, vcc
	v_pk_fma_f32 v[60:61], v[60:61], v[0:1], v[56:57] op_sel_hi:[1,0,1] neg_lo:[0,0,1] neg_hi:[0,0,1]
	v_pk_fma_f32 v[62:63], v[62:63], v[0:1], v[58:59] op_sel_hi:[1,0,1] neg_lo:[0,0,1] neg_hi:[0,0,1]
	ds_read_b128 v[202:205], v124 offset:21008
	ds_read_b128 v[198:201], v124 offset:20992
	v_pk_fma_f32 v[36:37], v[36:37], v[48:49], v[64:65]
	v_pk_fma_f32 v[38:39], v[38:39], v[50:51], v[66:67]
	v_pk_fma_f32 v[32:33], v[32:33], v[40:41], v[60:61]
	v_pk_fma_f32 v[34:35], v[34:35], v[42:43], v[62:63]
	s_waitcnt lgkmcnt(2)
	v_pk_mul_f32 v[156:157], v[32:33], v[156:157]
	v_pk_mul_f32 v[52:53], v[32:33], v[52:53]
	v_pk_mul_f32 v[158:159], v[34:35], v[158:159]
	v_pk_mul_f32 v[54:55], v[34:35], v[54:55]
	v_pk_fma_f32 v[152:153], v[36:37], v[152:153], v[156:157]
	v_pk_fma_f32 v[44:45], v[36:37], v[44:45], v[52:53]
	v_pk_fma_f32 v[154:155], v[38:39], v[154:155], v[158:159]
	v_pk_fma_f32 v[46:47], v[38:39], v[46:47], v[54:55]
	v_pk_add_f32 v[152:153], v[152:153], v[154:155]
	v_pk_add_f32 v[44:45], v[44:45], v[46:47]
	v_add_f32_e32 v142, v152, v153
	v_add_f32_e32 v143, v44, v45
	ds_read_b128 v[76:79], v124 offset:21776
	v_add_f32_dpp v142, v142, v142 quad_perm:[1,0,3,2] row_mask:0xf bank_mask:0xf bound_ctrl:1
	v_add_f32_dpp v143, v143, v143 quad_perm:[1,0,3,2] row_mask:0xf bank_mask:0xf bound_ctrl:1
	ds_read_b128 v[72:75], v124 offset:21760
	v_add_f32_dpp v142, v142, v142 quad_perm:[2,3,0,1] row_mask:0xf bank_mask:0xf bound_ctrl:1
	v_add_f32_dpp v143, v143, v143 quad_perm:[2,3,0,1] row_mask:0xf bank_mask:0xf bound_ctrl:1
	ds_read_b128 v[68:71], v124 offset:22016
	v_add_f32_dpp v142, v142, v142 row_half_mirror row_mask:0xf bank_mask:0xf bound_ctrl:1
	v_add_f32_dpp v143, v143, v143 row_half_mirror row_mask:0xf bank_mask:0xf bound_ctrl:1
	ds_read_b128 v[56:59], v124 offset:22032
	ds_read_b32 v0, v135 offset:22784
	ds_read_b128 v[64:67], v124 offset:22272
	ds_read_b128 v[60:63], v124 offset:22288
	ds_read_b128 v[48:51], v124 offset:21504
	ds_read_b128 v[40:43], v124 offset:21520
	v_pk_mul_f32 v[182:183], v[182:183], v[142:143] op_sel_hi:[1,0]
	v_pk_mul_f32 v[184:185], v[184:185], v[142:143] op_sel_hi:[1,0]
	s_lshl_b64 vcc, vcc, 1
	v_pk_mul_f32 v[186:187], v[186:187], v[142:143] op_sel_hi:[1,0]
	v_pk_mul_f32 v[188:189], v[188:189], v[142:143] op_sel_hi:[1,0]
	v_pk_fma_f32 v[190:191], v[190:191], v[160:161], v[182:183] op_sel_hi:[1,0,1] neg_lo:[0,0,1] neg_hi:[0,0,1]
	v_pk_fma_f32 v[192:193], v[192:193], v[160:161], v[184:185] op_sel_hi:[1,0,1] neg_lo:[0,0,1] neg_hi:[0,0,1]
	v_cndmask_b32_e32 v133, v133, v143, vcc
	v_pk_fma_f32 v[194:195], v[194:195], v[160:161], v[186:187] op_sel_hi:[1,0,1] neg_lo:[0,0,1] neg_hi:[0,0,1]
	v_pk_fma_f32 v[196:197], v[196:197], v[160:161], v[188:189] op_sel_hi:[1,0,1] neg_lo:[0,0,1] neg_hi:[0,0,1]
	ds_read_b128 v[52:55], v124 offset:22544
	ds_read_b128 v[44:47], v124 offset:22528
	v_pk_fma_f32 v[36:37], v[36:37], v[144:145], v[190:191]
	v_pk_fma_f32 v[38:39], v[38:39], v[146:147], v[192:193]
	v_pk_fma_f32 v[32:33], v[32:33], v[148:149], v[194:195]
	v_pk_fma_f32 v[34:35], v[34:35], v[150:151], v[196:197]
	s_waitcnt lgkmcnt(2)
	v_pk_mul_f32 v[76:77], v[32:33], v[76:77]
	v_pk_mul_f32 v[202:203], v[32:33], v[202:203]
	v_pk_mul_f32 v[78:79], v[34:35], v[78:79]
	v_pk_mul_f32 v[204:205], v[34:35], v[204:205]
	v_pk_fma_f32 v[72:73], v[36:37], v[72:73], v[76:77]
	v_pk_fma_f32 v[198:199], v[36:37], v[198:199], v[202:203]
	v_pk_fma_f32 v[74:75], v[38:39], v[74:75], v[78:79]
	v_pk_fma_f32 v[200:201], v[38:39], v[200:201], v[204:205]
	v_pk_add_f32 v[72:73], v[72:73], v[74:75]
	v_pk_add_f32 v[198:199], v[198:199], v[200:201]
	v_add_f32_e32 v142, v72, v73
	v_add_f32_e32 v143, v198, v199
	ds_read_b128 v[156:159], v124 offset:23312
	v_add_f32_dpp v142, v142, v142 quad_perm:[1,0,3,2] row_mask:0xf bank_mask:0xf bound_ctrl:1
	v_add_f32_dpp v143, v143, v143 quad_perm:[1,0,3,2] row_mask:0xf bank_mask:0xf bound_ctrl:1
	ds_read_b128 v[152:155], v124 offset:23296
	v_add_f32_dpp v142, v142, v142 quad_perm:[2,3,0,1] row_mask:0xf bank_mask:0xf bound_ctrl:1
	v_add_f32_dpp v143, v143, v143 quad_perm:[2,3,0,1] row_mask:0xf bank_mask:0xf bound_ctrl:1
	ds_read_b128 v[182:185], v124 offset:23552
	v_add_f32_dpp v142, v142, v142 row_half_mirror row_mask:0xf bank_mask:0xf bound_ctrl:1
	v_add_f32_dpp v143, v143, v143 row_half_mirror row_mask:0xf bank_mask:0xf bound_ctrl:1
	ds_read_b128 v[186:189], v124 offset:23568
	ds_read_b32 v160, v135 offset:24320
	ds_read_b128 v[190:193], v124 offset:23808
	ds_read_b128 v[194:197], v124 offset:23824
	ds_read_b128 v[144:147], v124 offset:23040
	ds_read_b128 v[148:151], v124 offset:23056
	v_pk_mul_f32 v[68:69], v[68:69], v[142:143] op_sel_hi:[1,0]
	v_pk_mul_f32 v[70:71], v[70:71], v[142:143] op_sel_hi:[1,0]
	s_lshl_b64 vcc, vcc, 1
	v_pk_mul_f32 v[56:57], v[56:57], v[142:143] op_sel_hi:[1,0]
	v_pk_mul_f32 v[58:59], v[58:59], v[142:143] op_sel_hi:[1,0]
	v_pk_fma_f32 v[64:65], v[64:65], v[0:1], v[68:69] op_sel_hi:[1,0,1] neg_lo:[0,0,1] neg_hi:[0,0,1]
	v_pk_fma_f32 v[66:67], v[66:67], v[0:1], v[70:71] op_sel_hi:[1,0,1] neg_lo:[0,0,1] neg_hi:[0,0,1]
	v_cndmask_b32_e32 v133, v133, v143, vcc
	v_pk_fma_f32 v[60:61], v[60:61], v[0:1], v[56:57] op_sel_hi:[1,0,1] neg_lo:[0,0,1] neg_hi:[0,0,1]
	v_pk_fma_f32 v[62:63], v[62:63], v[0:1], v[58:59] op_sel_hi:[1,0,1] neg_lo:[0,0,1] neg_hi:[0,0,1]
	ds_read_b128 v[202:205], v124 offset:24080
	ds_read_b128 v[198:201], v124 offset:24064
	v_pk_fma_f32 v[36:37], v[36:37], v[48:49], v[64:65]
	v_pk_fma_f32 v[38:39], v[38:39], v[50:51], v[66:67]
	v_pk_fma_f32 v[32:33], v[32:33], v[40:41], v[60:61]
	v_pk_fma_f32 v[34:35], v[34:35], v[42:43], v[62:63]
	s_waitcnt lgkmcnt(2)
	v_pk_mul_f32 v[156:157], v[32:33], v[156:157]
	v_pk_mul_f32 v[52:53], v[32:33], v[52:53]
	v_pk_mul_f32 v[158:159], v[34:35], v[158:159]
	v_pk_mul_f32 v[54:55], v[34:35], v[54:55]
	v_pk_fma_f32 v[152:153], v[36:37], v[152:153], v[156:157]
	v_pk_fma_f32 v[44:45], v[36:37], v[44:45], v[52:53]
	v_pk_fma_f32 v[154:155], v[38:39], v[154:155], v[158:159]
	v_pk_fma_f32 v[46:47], v[38:39], v[46:47], v[54:55]
	v_pk_add_f32 v[152:153], v[152:153], v[154:155]
	v_pk_add_f32 v[44:45], v[44:45], v[46:47]
	v_add_f32_e32 v142, v152, v153
	v_add_f32_e32 v143, v44, v45
	ds_read_b128 v[76:79], v124 offset:24848
	v_add_f32_dpp v142, v142, v142 quad_perm:[1,0,3,2] row_mask:0xf bank_mask:0xf bound_ctrl:1
	v_add_f32_dpp v143, v143, v143 quad_perm:[1,0,3,2] row_mask:0xf bank_mask:0xf bound_ctrl:1
	ds_read_b128 v[72:75], v124 offset:24832
	v_add_f32_dpp v142, v142, v142 quad_perm:[2,3,0,1] row_mask:0xf bank_mask:0xf bound_ctrl:1
	v_add_f32_dpp v143, v143, v143 quad_perm:[2,3,0,1] row_mask:0xf bank_mask:0xf bound_ctrl:1
	ds_read_b128 v[68:71], v124 offset:25088
	v_add_f32_dpp v142, v142, v142 row_half_mirror row_mask:0xf bank_mask:0xf bound_ctrl:1
	v_add_f32_dpp v143, v143, v143 row_half_mirror row_mask:0xf bank_mask:0xf bound_ctrl:1
	ds_read_b128 v[56:59], v124 offset:25104
	ds_read_b32 v0, v135 offset:25856
	ds_read_b128 v[64:67], v124 offset:25344
	ds_read_b128 v[60:63], v124 offset:25360
	ds_read_b128 v[48:51], v124 offset:24576
	ds_read_b128 v[40:43], v124 offset:24592
	v_pk_mul_f32 v[182:183], v[182:183], v[142:143] op_sel_hi:[1,0]
	v_pk_mul_f32 v[184:185], v[184:185], v[142:143] op_sel_hi:[1,0]
	s_lshl_b64 vcc, vcc, 1
	v_pk_mul_f32 v[186:187], v[186:187], v[142:143] op_sel_hi:[1,0]
	v_pk_mul_f32 v[188:189], v[188:189], v[142:143] op_sel_hi:[1,0]
	v_pk_fma_f32 v[190:191], v[190:191], v[160:161], v[182:183] op_sel_hi:[1,0,1] neg_lo:[0,0,1] neg_hi:[0,0,1]
	v_pk_fma_f32 v[192:193], v[192:193], v[160:161], v[184:185] op_sel_hi:[1,0,1] neg_lo:[0,0,1] neg_hi:[0,0,1]
	v_cndmask_b32_e32 v133, v133, v143, vcc
	v_pk_fma_f32 v[194:195], v[194:195], v[160:161], v[186:187] op_sel_hi:[1,0,1] neg_lo:[0,0,1] neg_hi:[0,0,1]
	v_pk_fma_f32 v[196:197], v[196:197], v[160:161], v[188:189] op_sel_hi:[1,0,1] neg_lo:[0,0,1] neg_hi:[0,0,1]
	ds_read_b128 v[52:55], v124 offset:25616
	ds_read_b128 v[44:47], v124 offset:25600
	v_pk_fma_f32 v[36:37], v[36:37], v[144:145], v[190:191]
	v_pk_fma_f32 v[38:39], v[38:39], v[146:147], v[192:193]
	v_pk_fma_f32 v[32:33], v[32:33], v[148:149], v[194:195]
	v_pk_fma_f32 v[34:35], v[34:35], v[150:151], v[196:197]
	s_waitcnt lgkmcnt(2)
	v_pk_mul_f32 v[76:77], v[32:33], v[76:77]
	v_pk_mul_f32 v[202:203], v[32:33], v[202:203]
	v_pk_mul_f32 v[78:79], v[34:35], v[78:79]
	v_pk_mul_f32 v[204:205], v[34:35], v[204:205]
	v_pk_fma_f32 v[72:73], v[36:37], v[72:73], v[76:77]
	v_pk_fma_f32 v[198:199], v[36:37], v[198:199], v[202:203]
	v_pk_fma_f32 v[74:75], v[38:39], v[74:75], v[78:79]
	v_pk_fma_f32 v[200:201], v[38:39], v[200:201], v[204:205]
	v_pk_add_f32 v[72:73], v[72:73], v[74:75]
	v_pk_add_f32 v[198:199], v[198:199], v[200:201]
	v_add_f32_e32 v142, v72, v73
	v_add_f32_e32 v143, v198, v199
	ds_read_b128 v[156:159], v124 offset:26384
	v_add_f32_dpp v142, v142, v142 quad_perm:[1,0,3,2] row_mask:0xf bank_mask:0xf bound_ctrl:1
	v_add_f32_dpp v143, v143, v143 quad_perm:[1,0,3,2] row_mask:0xf bank_mask:0xf bound_ctrl:1
	ds_read_b128 v[152:155], v124 offset:26368
	v_add_f32_dpp v142, v142, v142 quad_perm:[2,3,0,1] row_mask:0xf bank_mask:0xf bound_ctrl:1
	v_add_f32_dpp v143, v143, v143 quad_perm:[2,3,0,1] row_mask:0xf bank_mask:0xf bound_ctrl:1
	ds_read_b128 v[182:185], v124 offset:26624
	v_add_f32_dpp v142, v142, v142 row_half_mirror row_mask:0xf bank_mask:0xf bound_ctrl:1
	v_add_f32_dpp v143, v143, v143 row_half_mirror row_mask:0xf bank_mask:0xf bound_ctrl:1
	ds_read_b128 v[186:189], v124 offset:26640
	ds_read_b32 v160, v135 offset:27392
	ds_read_b128 v[190:193], v124 offset:26880
	ds_read_b128 v[194:197], v124 offset:26896
	ds_read_b128 v[144:147], v124 offset:26112
	ds_read_b128 v[148:151], v124 offset:26128
	v_pk_mul_f32 v[68:69], v[68:69], v[142:143] op_sel_hi:[1,0]
	v_pk_mul_f32 v[70:71], v[70:71], v[142:143] op_sel_hi:[1,0]
	s_lshl_b64 vcc, vcc, 1
	v_pk_mul_f32 v[56:57], v[56:57], v[142:143] op_sel_hi:[1,0]
	v_pk_mul_f32 v[58:59], v[58:59], v[142:143] op_sel_hi:[1,0]
	v_pk_fma_f32 v[64:65], v[64:65], v[0:1], v[68:69] op_sel_hi:[1,0,1] neg_lo:[0,0,1] neg_hi:[0,0,1]
	v_pk_fma_f32 v[66:67], v[66:67], v[0:1], v[70:71] op_sel_hi:[1,0,1] neg_lo:[0,0,1] neg_hi:[0,0,1]
	v_cndmask_b32_e32 v133, v133, v143, vcc
	v_pk_fma_f32 v[60:61], v[60:61], v[0:1], v[56:57] op_sel_hi:[1,0,1] neg_lo:[0,0,1] neg_hi:[0,0,1]
	v_pk_fma_f32 v[62:63], v[62:63], v[0:1], v[58:59] op_sel_hi:[1,0,1] neg_lo:[0,0,1] neg_hi:[0,0,1]
	ds_read_b128 v[202:205], v124 offset:27152
	ds_read_b128 v[198:201], v124 offset:27136
	v_pk_fma_f32 v[36:37], v[36:37], v[48:49], v[64:65]
	v_pk_fma_f32 v[38:39], v[38:39], v[50:51], v[66:67]
	v_pk_fma_f32 v[32:33], v[32:33], v[40:41], v[60:61]
	v_pk_fma_f32 v[34:35], v[34:35], v[42:43], v[62:63]
	s_waitcnt lgkmcnt(2)
	v_pk_mul_f32 v[156:157], v[32:33], v[156:157]
	v_pk_mul_f32 v[52:53], v[32:33], v[52:53]
	v_pk_mul_f32 v[158:159], v[34:35], v[158:159]
	v_pk_mul_f32 v[54:55], v[34:35], v[54:55]
	v_pk_fma_f32 v[152:153], v[36:37], v[152:153], v[156:157]
	v_pk_fma_f32 v[44:45], v[36:37], v[44:45], v[52:53]
	v_pk_fma_f32 v[154:155], v[38:39], v[154:155], v[158:159]
	v_pk_fma_f32 v[46:47], v[38:39], v[46:47], v[54:55]
	v_pk_add_f32 v[152:153], v[152:153], v[154:155]
	v_pk_add_f32 v[44:45], v[44:45], v[46:47]
	v_add_f32_e32 v142, v152, v153
	v_add_f32_e32 v143, v44, v45
	ds_read_b128 v[76:79], v124 offset:27920
	v_add_f32_dpp v142, v142, v142 quad_perm:[1,0,3,2] row_mask:0xf bank_mask:0xf bound_ctrl:1
	v_add_f32_dpp v143, v143, v143 quad_perm:[1,0,3,2] row_mask:0xf bank_mask:0xf bound_ctrl:1
	ds_read_b128 v[72:75], v124 offset:27904
	v_add_f32_dpp v142, v142, v142 quad_perm:[2,3,0,1] row_mask:0xf bank_mask:0xf bound_ctrl:1
	v_add_f32_dpp v143, v143, v143 quad_perm:[2,3,0,1] row_mask:0xf bank_mask:0xf bound_ctrl:1
	ds_read_b128 v[68:71], v124 offset:28160
	v_add_f32_dpp v142, v142, v142 row_half_mirror row_mask:0xf bank_mask:0xf bound_ctrl:1
	v_add_f32_dpp v143, v143, v143 row_half_mirror row_mask:0xf bank_mask:0xf bound_ctrl:1
	ds_read_b128 v[56:59], v124 offset:28176
	ds_read_b32 v0, v135 offset:28928
	ds_read_b128 v[64:67], v124 offset:28416
	ds_read_b128 v[60:63], v124 offset:28432
	ds_read_b128 v[48:51], v124 offset:27648
	ds_read_b128 v[40:43], v124 offset:27664
	v_pk_mul_f32 v[182:183], v[182:183], v[142:143] op_sel_hi:[1,0]
	v_pk_mul_f32 v[184:185], v[184:185], v[142:143] op_sel_hi:[1,0]
	s_mov_b32 vcc_lo, 0x1010101
	v_pk_mul_f32 v[186:187], v[186:187], v[142:143] op_sel_hi:[1,0]
	v_pk_mul_f32 v[188:189], v[188:189], v[142:143] op_sel_hi:[1,0]
	s_mov_b32 vcc_hi, 0x1010101
	v_pk_fma_f32 v[190:191], v[190:191], v[160:161], v[182:183] op_sel_hi:[1,0,1] neg_lo:[0,0,1] neg_hi:[0,0,1]
	v_pk_fma_f32 v[192:193], v[192:193], v[160:161], v[184:185] op_sel_hi:[1,0,1] neg_lo:[0,0,1] neg_hi:[0,0,1]
	v_cndmask_b32_e32 v132, v132, v143, vcc
	v_pk_fma_f32 v[194:195], v[194:195], v[160:161], v[186:187] op_sel_hi:[1,0,1] neg_lo:[0,0,1] neg_hi:[0,0,1]
	v_pk_fma_f32 v[196:197], v[196:197], v[160:161], v[188:189] op_sel_hi:[1,0,1] neg_lo:[0,0,1] neg_hi:[0,0,1]
	ds_read_b128 v[52:55], v124 offset:28688
	ds_read_b128 v[44:47], v124 offset:28672
	v_pk_fma_f32 v[36:37], v[36:37], v[144:145], v[190:191]
	v_pk_fma_f32 v[38:39], v[38:39], v[146:147], v[192:193]
	v_pk_fma_f32 v[32:33], v[32:33], v[148:149], v[194:195]
	v_pk_fma_f32 v[34:35], v[34:35], v[150:151], v[196:197]
	s_waitcnt lgkmcnt(2)
	v_pk_mul_f32 v[76:77], v[32:33], v[76:77]
	v_pk_mul_f32 v[202:203], v[32:33], v[202:203]
	v_pk_mul_f32 v[78:79], v[34:35], v[78:79]
	v_pk_mul_f32 v[204:205], v[34:35], v[204:205]
	v_pk_fma_f32 v[72:73], v[36:37], v[72:73], v[76:77]
	v_pk_fma_f32 v[198:199], v[36:37], v[198:199], v[202:203]
	v_pk_fma_f32 v[74:75], v[38:39], v[74:75], v[78:79]
	v_pk_fma_f32 v[200:201], v[38:39], v[200:201], v[204:205]
	v_pk_add_f32 v[72:73], v[72:73], v[74:75]
	v_pk_add_f32 v[198:199], v[198:199], v[200:201]
	v_add_f32_e32 v142, v72, v73
	v_add_f32_e32 v143, v198, v199
	ds_read_b128 v[156:159], v124 offset:29456
	v_add_f32_dpp v142, v142, v142 quad_perm:[1,0,3,2] row_mask:0xf bank_mask:0xf bound_ctrl:1
	v_add_f32_dpp v143, v143, v143 quad_perm:[1,0,3,2] row_mask:0xf bank_mask:0xf bound_ctrl:1
	ds_read_b128 v[152:155], v124 offset:29440
	v_add_f32_dpp v142, v142, v142 quad_perm:[2,3,0,1] row_mask:0xf bank_mask:0xf bound_ctrl:1
	v_add_f32_dpp v143, v143, v143 quad_perm:[2,3,0,1] row_mask:0xf bank_mask:0xf bound_ctrl:1
	ds_read_b128 v[182:185], v124 offset:29696
	v_add_f32_dpp v142, v142, v142 row_half_mirror row_mask:0xf bank_mask:0xf bound_ctrl:1
	v_add_f32_dpp v143, v143, v143 row_half_mirror row_mask:0xf bank_mask:0xf bound_ctrl:1
	ds_read_b128 v[186:189], v124 offset:29712
	ds_read_b32 v160, v135 offset:30464
	ds_read_b128 v[190:193], v124 offset:29952
	ds_read_b128 v[194:197], v124 offset:29968
	ds_read_b128 v[144:147], v124 offset:29184
	ds_read_b128 v[148:151], v124 offset:29200
	v_pk_mul_f32 v[68:69], v[68:69], v[142:143] op_sel_hi:[1,0]
	v_pk_mul_f32 v[70:71], v[70:71], v[142:143] op_sel_hi:[1,0]
	s_lshl_b64 vcc, vcc, 1
	v_pk_mul_f32 v[56:57], v[56:57], v[142:143] op_sel_hi:[1,0]
	v_pk_mul_f32 v[58:59], v[58:59], v[142:143] op_sel_hi:[1,0]
	v_pk_fma_f32 v[64:65], v[64:65], v[0:1], v[68:69] op_sel_hi:[1,0,1] neg_lo:[0,0,1] neg_hi:[0,0,1]
	v_pk_fma_f32 v[66:67], v[66:67], v[0:1], v[70:71] op_sel_hi:[1,0,1] neg_lo:[0,0,1] neg_hi:[0,0,1]
	v_cndmask_b32_e32 v132, v132, v143, vcc
	v_pk_fma_f32 v[60:61], v[60:61], v[0:1], v[56:57] op_sel_hi:[1,0,1] neg_lo:[0,0,1] neg_hi:[0,0,1]
	v_pk_fma_f32 v[62:63], v[62:63], v[0:1], v[58:59] op_sel_hi:[1,0,1] neg_lo:[0,0,1] neg_hi:[0,0,1]
	ds_read_b128 v[202:205], v124 offset:30224
	ds_read_b128 v[198:201], v124 offset:30208
	v_pk_fma_f32 v[36:37], v[36:37], v[48:49], v[64:65]
	v_pk_fma_f32 v[38:39], v[38:39], v[50:51], v[66:67]
	v_pk_fma_f32 v[32:33], v[32:33], v[40:41], v[60:61]
	v_pk_fma_f32 v[34:35], v[34:35], v[42:43], v[62:63]
	s_waitcnt lgkmcnt(2)
	v_pk_mul_f32 v[156:157], v[32:33], v[156:157]
	v_pk_mul_f32 v[52:53], v[32:33], v[52:53]
	v_pk_mul_f32 v[158:159], v[34:35], v[158:159]
	v_pk_mul_f32 v[54:55], v[34:35], v[54:55]
	v_pk_fma_f32 v[152:153], v[36:37], v[152:153], v[156:157]
	v_pk_fma_f32 v[44:45], v[36:37], v[44:45], v[52:53]
	v_pk_fma_f32 v[154:155], v[38:39], v[154:155], v[158:159]
	v_pk_fma_f32 v[46:47], v[38:39], v[46:47], v[54:55]
	v_pk_add_f32 v[152:153], v[152:153], v[154:155]
	v_pk_add_f32 v[44:45], v[44:45], v[46:47]
	v_add_f32_e32 v142, v152, v153
	v_add_f32_e32 v143, v44, v45
	ds_read_b128 v[76:79], v124 offset:30992
	v_add_f32_dpp v142, v142, v142 quad_perm:[1,0,3,2] row_mask:0xf bank_mask:0xf bound_ctrl:1
	v_add_f32_dpp v143, v143, v143 quad_perm:[1,0,3,2] row_mask:0xf bank_mask:0xf bound_ctrl:1
	ds_read_b128 v[72:75], v124 offset:30976
	v_add_f32_dpp v142, v142, v142 quad_perm:[2,3,0,1] row_mask:0xf bank_mask:0xf bound_ctrl:1
	v_add_f32_dpp v143, v143, v143 quad_perm:[2,3,0,1] row_mask:0xf bank_mask:0xf bound_ctrl:1
	ds_read_b128 v[68:71], v124 offset:31232
	v_add_f32_dpp v142, v142, v142 row_half_mirror row_mask:0xf bank_mask:0xf bound_ctrl:1
	v_add_f32_dpp v143, v143, v143 row_half_mirror row_mask:0xf bank_mask:0xf bound_ctrl:1
	ds_read_b128 v[56:59], v124 offset:31248
	ds_read_b32 v0, v135 offset:32000
	ds_read_b128 v[64:67], v124 offset:31488
	ds_read_b128 v[60:63], v124 offset:31504
	ds_read_b128 v[48:51], v124 offset:30720
	ds_read_b128 v[40:43], v124 offset:30736
	v_pk_mul_f32 v[182:183], v[182:183], v[142:143] op_sel_hi:[1,0]
	v_pk_mul_f32 v[184:185], v[184:185], v[142:143] op_sel_hi:[1,0]
	s_lshl_b64 vcc, vcc, 1
	v_pk_mul_f32 v[186:187], v[186:187], v[142:143] op_sel_hi:[1,0]
	v_pk_mul_f32 v[188:189], v[188:189], v[142:143] op_sel_hi:[1,0]
	v_pk_fma_f32 v[190:191], v[190:191], v[160:161], v[182:183] op_sel_hi:[1,0,1] neg_lo:[0,0,1] neg_hi:[0,0,1]
	v_pk_fma_f32 v[192:193], v[192:193], v[160:161], v[184:185] op_sel_hi:[1,0,1] neg_lo:[0,0,1] neg_hi:[0,0,1]
	v_cndmask_b32_e32 v132, v132, v143, vcc
	v_pk_fma_f32 v[194:195], v[194:195], v[160:161], v[186:187] op_sel_hi:[1,0,1] neg_lo:[0,0,1] neg_hi:[0,0,1]
	v_pk_fma_f32 v[196:197], v[196:197], v[160:161], v[188:189] op_sel_hi:[1,0,1] neg_lo:[0,0,1] neg_hi:[0,0,1]
	ds_read_b128 v[52:55], v124 offset:31760
	ds_read_b128 v[44:47], v124 offset:31744
	v_pk_fma_f32 v[36:37], v[36:37], v[144:145], v[190:191]
	v_pk_fma_f32 v[38:39], v[38:39], v[146:147], v[192:193]
	v_pk_fma_f32 v[32:33], v[32:33], v[148:149], v[194:195]
	v_pk_fma_f32 v[34:35], v[34:35], v[150:151], v[196:197]
	s_waitcnt lgkmcnt(2)
	v_pk_mul_f32 v[76:77], v[32:33], v[76:77]
	v_pk_mul_f32 v[202:203], v[32:33], v[202:203]
	v_pk_mul_f32 v[78:79], v[34:35], v[78:79]
	v_pk_mul_f32 v[204:205], v[34:35], v[204:205]
	v_pk_fma_f32 v[72:73], v[36:37], v[72:73], v[76:77]
	v_pk_fma_f32 v[198:199], v[36:37], v[198:199], v[202:203]
	v_pk_fma_f32 v[74:75], v[38:39], v[74:75], v[78:79]
	v_pk_fma_f32 v[200:201], v[38:39], v[200:201], v[204:205]
	v_pk_add_f32 v[72:73], v[72:73], v[74:75]
	v_pk_add_f32 v[198:199], v[198:199], v[200:201]
	v_add_f32_e32 v142, v72, v73
	v_add_f32_e32 v143, v198, v199
	ds_read_b128 v[156:159], v124 offset:32528
	v_add_f32_dpp v142, v142, v142 quad_perm:[1,0,3,2] row_mask:0xf bank_mask:0xf bound_ctrl:1
	v_add_f32_dpp v143, v143, v143 quad_perm:[1,0,3,2] row_mask:0xf bank_mask:0xf bound_ctrl:1
	ds_read_b128 v[152:155], v124 offset:32512
	v_add_f32_dpp v142, v142, v142 quad_perm:[2,3,0,1] row_mask:0xf bank_mask:0xf bound_ctrl:1
	v_add_f32_dpp v143, v143, v143 quad_perm:[2,3,0,1] row_mask:0xf bank_mask:0xf bound_ctrl:1
	ds_read_b128 v[182:185], v124 offset:32768
	v_add_f32_dpp v142, v142, v142 row_half_mirror row_mask:0xf bank_mask:0xf bound_ctrl:1
	v_add_f32_dpp v143, v143, v143 row_half_mirror row_mask:0xf bank_mask:0xf bound_ctrl:1
	ds_read_b128 v[186:189], v124 offset:32784
	ds_read_b32 v160, v135 offset:33536
	ds_read_b128 v[190:193], v124 offset:33024
	ds_read_b128 v[194:197], v124 offset:33040
	ds_read_b128 v[144:147], v124 offset:32256
	ds_read_b128 v[148:151], v124 offset:32272
	v_pk_mul_f32 v[68:69], v[68:69], v[142:143] op_sel_hi:[1,0]
	v_pk_mul_f32 v[70:71], v[70:71], v[142:143] op_sel_hi:[1,0]
	s_lshl_b64 vcc, vcc, 1
	v_pk_mul_f32 v[56:57], v[56:57], v[142:143] op_sel_hi:[1,0]
	v_pk_mul_f32 v[58:59], v[58:59], v[142:143] op_sel_hi:[1,0]
	v_pk_fma_f32 v[64:65], v[64:65], v[0:1], v[68:69] op_sel_hi:[1,0,1] neg_lo:[0,0,1] neg_hi:[0,0,1]
	v_pk_fma_f32 v[66:67], v[66:67], v[0:1], v[70:71] op_sel_hi:[1,0,1] neg_lo:[0,0,1] neg_hi:[0,0,1]
	v_cndmask_b32_e32 v132, v132, v143, vcc
	v_pk_fma_f32 v[60:61], v[60:61], v[0:1], v[56:57] op_sel_hi:[1,0,1] neg_lo:[0,0,1] neg_hi:[0,0,1]
	v_pk_fma_f32 v[62:63], v[62:63], v[0:1], v[58:59] op_sel_hi:[1,0,1] neg_lo:[0,0,1] neg_hi:[0,0,1]
	ds_read_b128 v[202:205], v124 offset:33296
	ds_read_b128 v[198:201], v124 offset:33280
	v_pk_fma_f32 v[36:37], v[36:37], v[48:49], v[64:65]
	v_pk_fma_f32 v[38:39], v[38:39], v[50:51], v[66:67]
	v_pk_fma_f32 v[32:33], v[32:33], v[40:41], v[60:61]
	v_pk_fma_f32 v[34:35], v[34:35], v[42:43], v[62:63]
	s_waitcnt lgkmcnt(2)
	v_pk_mul_f32 v[156:157], v[32:33], v[156:157]
	v_pk_mul_f32 v[52:53], v[32:33], v[52:53]
	v_pk_mul_f32 v[158:159], v[34:35], v[158:159]
	v_pk_mul_f32 v[54:55], v[34:35], v[54:55]
	v_pk_fma_f32 v[152:153], v[36:37], v[152:153], v[156:157]
	v_pk_fma_f32 v[44:45], v[36:37], v[44:45], v[52:53]
	v_pk_fma_f32 v[154:155], v[38:39], v[154:155], v[158:159]
	v_pk_fma_f32 v[46:47], v[38:39], v[46:47], v[54:55]
	v_pk_add_f32 v[152:153], v[152:153], v[154:155]
	v_pk_add_f32 v[44:45], v[44:45], v[46:47]
	v_add_f32_e32 v142, v152, v153
	v_add_f32_e32 v143, v44, v45
	ds_read_b128 v[76:79], v124 offset:34064
	v_add_f32_dpp v142, v142, v142 quad_perm:[1,0,3,2] row_mask:0xf bank_mask:0xf bound_ctrl:1
	v_add_f32_dpp v143, v143, v143 quad_perm:[1,0,3,2] row_mask:0xf bank_mask:0xf bound_ctrl:1
	ds_read_b128 v[72:75], v124 offset:34048
	v_add_f32_dpp v142, v142, v142 quad_perm:[2,3,0,1] row_mask:0xf bank_mask:0xf bound_ctrl:1
	v_add_f32_dpp v143, v143, v143 quad_perm:[2,3,0,1] row_mask:0xf bank_mask:0xf bound_ctrl:1
	ds_read_b128 v[68:71], v124 offset:34304
	v_add_f32_dpp v142, v142, v142 row_half_mirror row_mask:0xf bank_mask:0xf bound_ctrl:1
	v_add_f32_dpp v143, v143, v143 row_half_mirror row_mask:0xf bank_mask:0xf bound_ctrl:1
	ds_read_b128 v[56:59], v124 offset:34320
	ds_read_b32 v0, v135 offset:35072
	ds_read_b128 v[64:67], v124 offset:34560
	ds_read_b128 v[60:63], v124 offset:34576
	ds_read_b128 v[48:51], v124 offset:33792
	ds_read_b128 v[40:43], v124 offset:33808
	v_pk_mul_f32 v[182:183], v[182:183], v[142:143] op_sel_hi:[1,0]
	v_pk_mul_f32 v[184:185], v[184:185], v[142:143] op_sel_hi:[1,0]
	s_lshl_b64 vcc, vcc, 1
	v_pk_mul_f32 v[186:187], v[186:187], v[142:143] op_sel_hi:[1,0]
	v_pk_mul_f32 v[188:189], v[188:189], v[142:143] op_sel_hi:[1,0]
	v_pk_fma_f32 v[190:191], v[190:191], v[160:161], v[182:183] op_sel_hi:[1,0,1] neg_lo:[0,0,1] neg_hi:[0,0,1]
	v_pk_fma_f32 v[192:193], v[192:193], v[160:161], v[184:185] op_sel_hi:[1,0,1] neg_lo:[0,0,1] neg_hi:[0,0,1]
	v_cndmask_b32_e32 v132, v132, v143, vcc
	v_pk_fma_f32 v[194:195], v[194:195], v[160:161], v[186:187] op_sel_hi:[1,0,1] neg_lo:[0,0,1] neg_hi:[0,0,1]
	v_pk_fma_f32 v[196:197], v[196:197], v[160:161], v[188:189] op_sel_hi:[1,0,1] neg_lo:[0,0,1] neg_hi:[0,0,1]
	ds_read_b128 v[52:55], v124 offset:34832
	ds_read_b128 v[44:47], v124 offset:34816
	v_pk_fma_f32 v[36:37], v[36:37], v[144:145], v[190:191]
	v_pk_fma_f32 v[38:39], v[38:39], v[146:147], v[192:193]
	v_pk_fma_f32 v[32:33], v[32:33], v[148:149], v[194:195]
	v_pk_fma_f32 v[34:35], v[34:35], v[150:151], v[196:197]
	s_waitcnt lgkmcnt(2)
	v_pk_mul_f32 v[76:77], v[32:33], v[76:77]
	v_pk_mul_f32 v[202:203], v[32:33], v[202:203]
	v_pk_mul_f32 v[78:79], v[34:35], v[78:79]
	v_pk_mul_f32 v[204:205], v[34:35], v[204:205]
	v_pk_fma_f32 v[72:73], v[36:37], v[72:73], v[76:77]
	v_pk_fma_f32 v[198:199], v[36:37], v[198:199], v[202:203]
	v_pk_fma_f32 v[74:75], v[38:39], v[74:75], v[78:79]
	v_pk_fma_f32 v[200:201], v[38:39], v[200:201], v[204:205]
	v_pk_add_f32 v[72:73], v[72:73], v[74:75]
	v_pk_add_f32 v[198:199], v[198:199], v[200:201]
	v_add_f32_e32 v142, v72, v73
	v_add_f32_e32 v143, v198, v199
	ds_read_b128 v[156:159], v124 offset:35600
	v_add_f32_dpp v142, v142, v142 quad_perm:[1,0,3,2] row_mask:0xf bank_mask:0xf bound_ctrl:1
	v_add_f32_dpp v143, v143, v143 quad_perm:[1,0,3,2] row_mask:0xf bank_mask:0xf bound_ctrl:1
	ds_read_b128 v[152:155], v124 offset:35584
	v_add_f32_dpp v142, v142, v142 quad_perm:[2,3,0,1] row_mask:0xf bank_mask:0xf bound_ctrl:1
	v_add_f32_dpp v143, v143, v143 quad_perm:[2,3,0,1] row_mask:0xf bank_mask:0xf bound_ctrl:1
	ds_read_b128 v[182:185], v124 offset:35840
	v_add_f32_dpp v142, v142, v142 row_half_mirror row_mask:0xf bank_mask:0xf bound_ctrl:1
	v_add_f32_dpp v143, v143, v143 row_half_mirror row_mask:0xf bank_mask:0xf bound_ctrl:1
	ds_read_b128 v[186:189], v124 offset:35856
	ds_read_b32 v160, v135 offset:36608
	ds_read_b128 v[190:193], v124 offset:36096
	ds_read_b128 v[194:197], v124 offset:36112
	ds_read_b128 v[144:147], v124 offset:35328
	ds_read_b128 v[148:151], v124 offset:35344
	v_pk_mul_f32 v[68:69], v[68:69], v[142:143] op_sel_hi:[1,0]
	v_pk_mul_f32 v[70:71], v[70:71], v[142:143] op_sel_hi:[1,0]
	s_lshl_b64 vcc, vcc, 1
	v_pk_mul_f32 v[56:57], v[56:57], v[142:143] op_sel_hi:[1,0]
	v_pk_mul_f32 v[58:59], v[58:59], v[142:143] op_sel_hi:[1,0]
	v_pk_fma_f32 v[64:65], v[64:65], v[0:1], v[68:69] op_sel_hi:[1,0,1] neg_lo:[0,0,1] neg_hi:[0,0,1]
	v_pk_fma_f32 v[66:67], v[66:67], v[0:1], v[70:71] op_sel_hi:[1,0,1] neg_lo:[0,0,1] neg_hi:[0,0,1]
	v_cndmask_b32_e32 v132, v132, v143, vcc
	v_pk_fma_f32 v[60:61], v[60:61], v[0:1], v[56:57] op_sel_hi:[1,0,1] neg_lo:[0,0,1] neg_hi:[0,0,1]
	v_pk_fma_f32 v[62:63], v[62:63], v[0:1], v[58:59] op_sel_hi:[1,0,1] neg_lo:[0,0,1] neg_hi:[0,0,1]
	ds_read_b128 v[202:205], v124 offset:36368
	ds_read_b128 v[198:201], v124 offset:36352
	v_pk_fma_f32 v[36:37], v[36:37], v[48:49], v[64:65]
	v_pk_fma_f32 v[38:39], v[38:39], v[50:51], v[66:67]
	v_pk_fma_f32 v[32:33], v[32:33], v[40:41], v[60:61]
	v_pk_fma_f32 v[34:35], v[34:35], v[42:43], v[62:63]
	s_waitcnt lgkmcnt(2)
	v_pk_mul_f32 v[156:157], v[32:33], v[156:157]
	v_pk_mul_f32 v[52:53], v[32:33], v[52:53]
	v_pk_mul_f32 v[158:159], v[34:35], v[158:159]
	v_pk_mul_f32 v[54:55], v[34:35], v[54:55]
	v_pk_fma_f32 v[152:153], v[36:37], v[152:153], v[156:157]
	v_pk_fma_f32 v[44:45], v[36:37], v[44:45], v[52:53]
	v_pk_fma_f32 v[154:155], v[38:39], v[154:155], v[158:159]
	v_pk_fma_f32 v[46:47], v[38:39], v[46:47], v[54:55]
	v_pk_add_f32 v[152:153], v[152:153], v[154:155]
	v_pk_add_f32 v[44:45], v[44:45], v[46:47]
	v_add_f32_e32 v142, v152, v153
	v_add_f32_e32 v143, v44, v45
	ds_read_b128 v[76:79], v124 offset:37136
	v_add_f32_dpp v142, v142, v142 quad_perm:[1,0,3,2] row_mask:0xf bank_mask:0xf bound_ctrl:1
	v_add_f32_dpp v143, v143, v143 quad_perm:[1,0,3,2] row_mask:0xf bank_mask:0xf bound_ctrl:1
	ds_read_b128 v[72:75], v124 offset:37120
	v_add_f32_dpp v142, v142, v142 quad_perm:[2,3,0,1] row_mask:0xf bank_mask:0xf bound_ctrl:1
	v_add_f32_dpp v143, v143, v143 quad_perm:[2,3,0,1] row_mask:0xf bank_mask:0xf bound_ctrl:1
	ds_read_b128 v[68:71], v124 offset:37376
	v_add_f32_dpp v142, v142, v142 row_half_mirror row_mask:0xf bank_mask:0xf bound_ctrl:1
	v_add_f32_dpp v143, v143, v143 row_half_mirror row_mask:0xf bank_mask:0xf bound_ctrl:1
	ds_read_b128 v[56:59], v124 offset:37392
	ds_read_b32 v0, v135 offset:38144
	ds_read_b128 v[64:67], v124 offset:37632
	ds_read_b128 v[60:63], v124 offset:37648
	ds_read_b128 v[48:51], v124 offset:36864
	ds_read_b128 v[40:43], v124 offset:36880
	v_pk_mul_f32 v[182:183], v[182:183], v[142:143] op_sel_hi:[1,0]
	v_pk_mul_f32 v[184:185], v[184:185], v[142:143] op_sel_hi:[1,0]
	s_lshl_b64 vcc, vcc, 1
	v_pk_mul_f32 v[186:187], v[186:187], v[142:143] op_sel_hi:[1,0]
	v_pk_mul_f32 v[188:189], v[188:189], v[142:143] op_sel_hi:[1,0]
	v_pk_fma_f32 v[190:191], v[190:191], v[160:161], v[182:183] op_sel_hi:[1,0,1] neg_lo:[0,0,1] neg_hi:[0,0,1]
	v_pk_fma_f32 v[192:193], v[192:193], v[160:161], v[184:185] op_sel_hi:[1,0,1] neg_lo:[0,0,1] neg_hi:[0,0,1]
	v_cndmask_b32_e32 v132, v132, v143, vcc
	v_pk_fma_f32 v[194:195], v[194:195], v[160:161], v[186:187] op_sel_hi:[1,0,1] neg_lo:[0,0,1] neg_hi:[0,0,1]
	v_pk_fma_f32 v[196:197], v[196:197], v[160:161], v[188:189] op_sel_hi:[1,0,1] neg_lo:[0,0,1] neg_hi:[0,0,1]
	ds_read_b128 v[52:55], v124 offset:37904
	ds_read_b128 v[44:47], v124 offset:37888
	v_pk_fma_f32 v[36:37], v[36:37], v[144:145], v[190:191]
	v_pk_fma_f32 v[38:39], v[38:39], v[146:147], v[192:193]
	v_pk_fma_f32 v[32:33], v[32:33], v[148:149], v[194:195]
	v_pk_fma_f32 v[34:35], v[34:35], v[150:151], v[196:197]
	s_waitcnt lgkmcnt(2)
	v_pk_mul_f32 v[76:77], v[32:33], v[76:77]
	v_pk_mul_f32 v[202:203], v[32:33], v[202:203]
	v_pk_mul_f32 v[78:79], v[34:35], v[78:79]
	v_pk_mul_f32 v[204:205], v[34:35], v[204:205]
	v_pk_fma_f32 v[72:73], v[36:37], v[72:73], v[76:77]
	v_pk_fma_f32 v[198:199], v[36:37], v[198:199], v[202:203]
	v_pk_fma_f32 v[74:75], v[38:39], v[74:75], v[78:79]
	v_pk_fma_f32 v[200:201], v[38:39], v[200:201], v[204:205]
	v_pk_add_f32 v[72:73], v[72:73], v[74:75]
	v_pk_add_f32 v[198:199], v[198:199], v[200:201]
	v_add_f32_e32 v142, v72, v73
	v_add_f32_e32 v143, v198, v199
	ds_read_b128 v[156:159], v124 offset:38672
	v_add_f32_dpp v142, v142, v142 quad_perm:[1,0,3,2] row_mask:0xf bank_mask:0xf bound_ctrl:1
	v_add_f32_dpp v143, v143, v143 quad_perm:[1,0,3,2] row_mask:0xf bank_mask:0xf bound_ctrl:1
	ds_read_b128 v[152:155], v124 offset:38656
	v_add_f32_dpp v142, v142, v142 quad_perm:[2,3,0,1] row_mask:0xf bank_mask:0xf bound_ctrl:1
	v_add_f32_dpp v143, v143, v143 quad_perm:[2,3,0,1] row_mask:0xf bank_mask:0xf bound_ctrl:1
	ds_read_b128 v[182:185], v124 offset:38912
	v_add_f32_dpp v142, v142, v142 row_half_mirror row_mask:0xf bank_mask:0xf bound_ctrl:1
	v_add_f32_dpp v143, v143, v143 row_half_mirror row_mask:0xf bank_mask:0xf bound_ctrl:1
	ds_read_b128 v[186:189], v124 offset:38928
	ds_read_b32 v160, v135 offset:39680
	ds_read_b128 v[190:193], v124 offset:39168
	ds_read_b128 v[194:197], v124 offset:39184
	ds_read_b128 v[144:147], v124 offset:38400
	ds_read_b128 v[148:151], v124 offset:38416
	v_pk_mul_f32 v[68:69], v[68:69], v[142:143] op_sel_hi:[1,0]
	v_pk_mul_f32 v[70:71], v[70:71], v[142:143] op_sel_hi:[1,0]
	s_lshl_b64 vcc, vcc, 1
	v_pk_mul_f32 v[56:57], v[56:57], v[142:143] op_sel_hi:[1,0]
	v_pk_mul_f32 v[58:59], v[58:59], v[142:143] op_sel_hi:[1,0]
	v_pk_fma_f32 v[64:65], v[64:65], v[0:1], v[68:69] op_sel_hi:[1,0,1] neg_lo:[0,0,1] neg_hi:[0,0,1]
	v_pk_fma_f32 v[66:67], v[66:67], v[0:1], v[70:71] op_sel_hi:[1,0,1] neg_lo:[0,0,1] neg_hi:[0,0,1]
	v_cndmask_b32_e32 v132, v132, v143, vcc
	v_pk_fma_f32 v[60:61], v[60:61], v[0:1], v[56:57] op_sel_hi:[1,0,1] neg_lo:[0,0,1] neg_hi:[0,0,1]
	v_pk_fma_f32 v[62:63], v[62:63], v[0:1], v[58:59] op_sel_hi:[1,0,1] neg_lo:[0,0,1] neg_hi:[0,0,1]
	ds_read_b128 v[202:205], v124 offset:39440
	ds_read_b128 v[198:201], v124 offset:39424
	v_pk_fma_f32 v[36:37], v[36:37], v[48:49], v[64:65]
	v_pk_fma_f32 v[38:39], v[38:39], v[50:51], v[66:67]
	v_pk_fma_f32 v[32:33], v[32:33], v[40:41], v[60:61]
	v_pk_fma_f32 v[34:35], v[34:35], v[42:43], v[62:63]
	s_waitcnt lgkmcnt(2)
	v_pk_mul_f32 v[156:157], v[32:33], v[156:157]
	v_pk_mul_f32 v[52:53], v[32:33], v[52:53]
	v_pk_mul_f32 v[158:159], v[34:35], v[158:159]
	v_pk_mul_f32 v[54:55], v[34:35], v[54:55]
	v_pk_fma_f32 v[152:153], v[36:37], v[152:153], v[156:157]
	v_pk_fma_f32 v[44:45], v[36:37], v[44:45], v[52:53]
	v_pk_fma_f32 v[154:155], v[38:39], v[154:155], v[158:159]
	v_pk_fma_f32 v[46:47], v[38:39], v[46:47], v[54:55]
	v_pk_add_f32 v[152:153], v[152:153], v[154:155]
	v_pk_add_f32 v[44:45], v[44:45], v[46:47]
	v_add_f32_e32 v142, v152, v153
	v_add_f32_e32 v143, v44, v45
	ds_read_b128 v[76:79], v124 offset:40208
	v_add_f32_dpp v142, v142, v142 quad_perm:[1,0,3,2] row_mask:0xf bank_mask:0xf bound_ctrl:1
	v_add_f32_dpp v143, v143, v143 quad_perm:[1,0,3,2] row_mask:0xf bank_mask:0xf bound_ctrl:1
	ds_read_b128 v[72:75], v124 offset:40192
	v_add_f32_dpp v142, v142, v142 quad_perm:[2,3,0,1] row_mask:0xf bank_mask:0xf bound_ctrl:1
	v_add_f32_dpp v143, v143, v143 quad_perm:[2,3,0,1] row_mask:0xf bank_mask:0xf bound_ctrl:1
	ds_read_b128 v[68:71], v124 offset:40448
	v_add_f32_dpp v142, v142, v142 row_half_mirror row_mask:0xf bank_mask:0xf bound_ctrl:1
	v_add_f32_dpp v143, v143, v143 row_half_mirror row_mask:0xf bank_mask:0xf bound_ctrl:1
	ds_read_b128 v[56:59], v124 offset:40464
	ds_read_b32 v0, v135 offset:41216
	ds_read_b128 v[64:67], v124 offset:40704
	ds_read_b128 v[60:63], v124 offset:40720
	ds_read_b128 v[48:51], v124 offset:39936
	ds_read_b128 v[40:43], v124 offset:39952
	v_pk_mul_f32 v[182:183], v[182:183], v[142:143] op_sel_hi:[1,0]
	v_pk_mul_f32 v[184:185], v[184:185], v[142:143] op_sel_hi:[1,0]
	s_mov_b32 vcc_lo, 0x1010101
	v_pk_mul_f32 v[186:187], v[186:187], v[142:143] op_sel_hi:[1,0]
	v_pk_mul_f32 v[188:189], v[188:189], v[142:143] op_sel_hi:[1,0]
	s_mov_b32 vcc_hi, 0x1010101
	v_pk_fma_f32 v[190:191], v[190:191], v[160:161], v[182:183] op_sel_hi:[1,0,1] neg_lo:[0,0,1] neg_hi:[0,0,1]
	v_pk_fma_f32 v[192:193], v[192:193], v[160:161], v[184:185] op_sel_hi:[1,0,1] neg_lo:[0,0,1] neg_hi:[0,0,1]
	v_cndmask_b32_e32 v131, v131, v143, vcc
	v_pk_fma_f32 v[194:195], v[194:195], v[160:161], v[186:187] op_sel_hi:[1,0,1] neg_lo:[0,0,1] neg_hi:[0,0,1]
	v_pk_fma_f32 v[196:197], v[196:197], v[160:161], v[188:189] op_sel_hi:[1,0,1] neg_lo:[0,0,1] neg_hi:[0,0,1]
	ds_read_b128 v[52:55], v124 offset:40976
	ds_read_b128 v[44:47], v124 offset:40960
	v_pk_fma_f32 v[36:37], v[36:37], v[144:145], v[190:191]
	v_pk_fma_f32 v[38:39], v[38:39], v[146:147], v[192:193]
	v_pk_fma_f32 v[32:33], v[32:33], v[148:149], v[194:195]
	v_pk_fma_f32 v[34:35], v[34:35], v[150:151], v[196:197]
	s_waitcnt lgkmcnt(2)
	v_pk_mul_f32 v[76:77], v[32:33], v[76:77]
	v_pk_mul_f32 v[202:203], v[32:33], v[202:203]
	v_pk_mul_f32 v[78:79], v[34:35], v[78:79]
	v_pk_mul_f32 v[204:205], v[34:35], v[204:205]
	v_pk_fma_f32 v[72:73], v[36:37], v[72:73], v[76:77]
	v_pk_fma_f32 v[198:199], v[36:37], v[198:199], v[202:203]
	v_pk_fma_f32 v[74:75], v[38:39], v[74:75], v[78:79]
	v_pk_fma_f32 v[200:201], v[38:39], v[200:201], v[204:205]
	v_pk_add_f32 v[72:73], v[72:73], v[74:75]
	v_pk_add_f32 v[198:199], v[198:199], v[200:201]
	v_add_f32_e32 v142, v72, v73
	v_add_f32_e32 v143, v198, v199
	ds_read_b128 v[156:159], v124 offset:41744
	v_add_f32_dpp v142, v142, v142 quad_perm:[1,0,3,2] row_mask:0xf bank_mask:0xf bound_ctrl:1
	v_add_f32_dpp v143, v143, v143 quad_perm:[1,0,3,2] row_mask:0xf bank_mask:0xf bound_ctrl:1
	ds_read_b128 v[152:155], v124 offset:41728
	v_add_f32_dpp v142, v142, v142 quad_perm:[2,3,0,1] row_mask:0xf bank_mask:0xf bound_ctrl:1
	v_add_f32_dpp v143, v143, v143 quad_perm:[2,3,0,1] row_mask:0xf bank_mask:0xf bound_ctrl:1
	ds_read_b128 v[182:185], v124 offset:41984
	v_add_f32_dpp v142, v142, v142 row_half_mirror row_mask:0xf bank_mask:0xf bound_ctrl:1
	v_add_f32_dpp v143, v143, v143 row_half_mirror row_mask:0xf bank_mask:0xf bound_ctrl:1
	ds_read_b128 v[186:189], v124 offset:42000
	ds_read_b32 v160, v135 offset:42752
	ds_read_b128 v[190:193], v124 offset:42240
	ds_read_b128 v[194:197], v124 offset:42256
	ds_read_b128 v[144:147], v124 offset:41472
	ds_read_b128 v[148:151], v124 offset:41488
	v_pk_mul_f32 v[68:69], v[68:69], v[142:143] op_sel_hi:[1,0]
	v_pk_mul_f32 v[70:71], v[70:71], v[142:143] op_sel_hi:[1,0]
	s_lshl_b64 vcc, vcc, 1
	v_pk_mul_f32 v[56:57], v[56:57], v[142:143] op_sel_hi:[1,0]
	v_pk_mul_f32 v[58:59], v[58:59], v[142:143] op_sel_hi:[1,0]
	v_pk_fma_f32 v[64:65], v[64:65], v[0:1], v[68:69] op_sel_hi:[1,0,1] neg_lo:[0,0,1] neg_hi:[0,0,1]
	v_pk_fma_f32 v[66:67], v[66:67], v[0:1], v[70:71] op_sel_hi:[1,0,1] neg_lo:[0,0,1] neg_hi:[0,0,1]
	v_cndmask_b32_e32 v131, v131, v143, vcc
	v_pk_fma_f32 v[60:61], v[60:61], v[0:1], v[56:57] op_sel_hi:[1,0,1] neg_lo:[0,0,1] neg_hi:[0,0,1]
	v_pk_fma_f32 v[62:63], v[62:63], v[0:1], v[58:59] op_sel_hi:[1,0,1] neg_lo:[0,0,1] neg_hi:[0,0,1]
	ds_read_b128 v[202:205], v124 offset:42512
	ds_read_b128 v[198:201], v124 offset:42496
	v_pk_fma_f32 v[36:37], v[36:37], v[48:49], v[64:65]
	v_pk_fma_f32 v[38:39], v[38:39], v[50:51], v[66:67]
	v_pk_fma_f32 v[32:33], v[32:33], v[40:41], v[60:61]
	v_pk_fma_f32 v[34:35], v[34:35], v[42:43], v[62:63]
	s_waitcnt lgkmcnt(2)
	v_pk_mul_f32 v[156:157], v[32:33], v[156:157]
	v_pk_mul_f32 v[52:53], v[32:33], v[52:53]
	v_pk_mul_f32 v[158:159], v[34:35], v[158:159]
	v_pk_mul_f32 v[54:55], v[34:35], v[54:55]
	v_pk_fma_f32 v[152:153], v[36:37], v[152:153], v[156:157]
	v_pk_fma_f32 v[44:45], v[36:37], v[44:45], v[52:53]
	v_pk_fma_f32 v[154:155], v[38:39], v[154:155], v[158:159]
	v_pk_fma_f32 v[46:47], v[38:39], v[46:47], v[54:55]
	v_pk_add_f32 v[152:153], v[152:153], v[154:155]
	v_pk_add_f32 v[44:45], v[44:45], v[46:47]
	v_add_f32_e32 v142, v152, v153
	v_add_f32_e32 v143, v44, v45
	ds_read_b128 v[76:79], v124 offset:43280
	v_add_f32_dpp v142, v142, v142 quad_perm:[1,0,3,2] row_mask:0xf bank_mask:0xf bound_ctrl:1
	v_add_f32_dpp v143, v143, v143 quad_perm:[1,0,3,2] row_mask:0xf bank_mask:0xf bound_ctrl:1
	ds_read_b128 v[72:75], v124 offset:43264
	v_add_f32_dpp v142, v142, v142 quad_perm:[2,3,0,1] row_mask:0xf bank_mask:0xf bound_ctrl:1
	v_add_f32_dpp v143, v143, v143 quad_perm:[2,3,0,1] row_mask:0xf bank_mask:0xf bound_ctrl:1
	ds_read_b128 v[68:71], v124 offset:43520
	v_add_f32_dpp v142, v142, v142 row_half_mirror row_mask:0xf bank_mask:0xf bound_ctrl:1
	v_add_f32_dpp v143, v143, v143 row_half_mirror row_mask:0xf bank_mask:0xf bound_ctrl:1
	ds_read_b128 v[56:59], v124 offset:43536
	ds_read_b32 v0, v135 offset:44288
	ds_read_b128 v[64:67], v124 offset:43776
	ds_read_b128 v[60:63], v124 offset:43792
	ds_read_b128 v[48:51], v124 offset:43008
	ds_read_b128 v[40:43], v124 offset:43024
	v_pk_mul_f32 v[182:183], v[182:183], v[142:143] op_sel_hi:[1,0]
	v_pk_mul_f32 v[184:185], v[184:185], v[142:143] op_sel_hi:[1,0]
	s_lshl_b64 vcc, vcc, 1
	v_pk_mul_f32 v[186:187], v[186:187], v[142:143] op_sel_hi:[1,0]
	v_pk_mul_f32 v[188:189], v[188:189], v[142:143] op_sel_hi:[1,0]
	v_pk_fma_f32 v[190:191], v[190:191], v[160:161], v[182:183] op_sel_hi:[1,0,1] neg_lo:[0,0,1] neg_hi:[0,0,1]
	v_pk_fma_f32 v[192:193], v[192:193], v[160:161], v[184:185] op_sel_hi:[1,0,1] neg_lo:[0,0,1] neg_hi:[0,0,1]
	v_cndmask_b32_e32 v131, v131, v143, vcc
	v_pk_fma_f32 v[194:195], v[194:195], v[160:161], v[186:187] op_sel_hi:[1,0,1] neg_lo:[0,0,1] neg_hi:[0,0,1]
	v_pk_fma_f32 v[196:197], v[196:197], v[160:161], v[188:189] op_sel_hi:[1,0,1] neg_lo:[0,0,1] neg_hi:[0,0,1]
	ds_read_b128 v[52:55], v124 offset:44048
	ds_read_b128 v[44:47], v124 offset:44032
	v_pk_fma_f32 v[36:37], v[36:37], v[144:145], v[190:191]
	v_pk_fma_f32 v[38:39], v[38:39], v[146:147], v[192:193]
	v_pk_fma_f32 v[32:33], v[32:33], v[148:149], v[194:195]
	v_pk_fma_f32 v[34:35], v[34:35], v[150:151], v[196:197]
	s_waitcnt lgkmcnt(2)
	v_pk_mul_f32 v[76:77], v[32:33], v[76:77]
	v_pk_mul_f32 v[202:203], v[32:33], v[202:203]
	v_pk_mul_f32 v[78:79], v[34:35], v[78:79]
	v_pk_mul_f32 v[204:205], v[34:35], v[204:205]
	v_pk_fma_f32 v[72:73], v[36:37], v[72:73], v[76:77]
	v_pk_fma_f32 v[198:199], v[36:37], v[198:199], v[202:203]
	v_pk_fma_f32 v[74:75], v[38:39], v[74:75], v[78:79]
	v_pk_fma_f32 v[200:201], v[38:39], v[200:201], v[204:205]
	v_pk_add_f32 v[72:73], v[72:73], v[74:75]
	v_pk_add_f32 v[198:199], v[198:199], v[200:201]
	v_add_f32_e32 v142, v72, v73
	v_add_f32_e32 v143, v198, v199
	ds_read_b128 v[156:159], v124 offset:44816
	v_add_f32_dpp v142, v142, v142 quad_perm:[1,0,3,2] row_mask:0xf bank_mask:0xf bound_ctrl:1
	v_add_f32_dpp v143, v143, v143 quad_perm:[1,0,3,2] row_mask:0xf bank_mask:0xf bound_ctrl:1
	ds_read_b128 v[152:155], v124 offset:44800
	v_add_f32_dpp v142, v142, v142 quad_perm:[2,3,0,1] row_mask:0xf bank_mask:0xf bound_ctrl:1
	v_add_f32_dpp v143, v143, v143 quad_perm:[2,3,0,1] row_mask:0xf bank_mask:0xf bound_ctrl:1
	ds_read_b128 v[182:185], v124 offset:45056
	v_add_f32_dpp v142, v142, v142 row_half_mirror row_mask:0xf bank_mask:0xf bound_ctrl:1
	v_add_f32_dpp v143, v143, v143 row_half_mirror row_mask:0xf bank_mask:0xf bound_ctrl:1
	ds_read_b128 v[186:189], v124 offset:45072
	ds_read_b32 v160, v135 offset:45824
	ds_read_b128 v[190:193], v124 offset:45312
	ds_read_b128 v[194:197], v124 offset:45328
	ds_read_b128 v[144:147], v124 offset:44544
	ds_read_b128 v[148:151], v124 offset:44560
	v_pk_mul_f32 v[68:69], v[68:69], v[142:143] op_sel_hi:[1,0]
	v_pk_mul_f32 v[70:71], v[70:71], v[142:143] op_sel_hi:[1,0]
	s_lshl_b64 vcc, vcc, 1
	v_pk_mul_f32 v[56:57], v[56:57], v[142:143] op_sel_hi:[1,0]
	v_pk_mul_f32 v[58:59], v[58:59], v[142:143] op_sel_hi:[1,0]
	v_pk_fma_f32 v[64:65], v[64:65], v[0:1], v[68:69] op_sel_hi:[1,0,1] neg_lo:[0,0,1] neg_hi:[0,0,1]
	v_pk_fma_f32 v[66:67], v[66:67], v[0:1], v[70:71] op_sel_hi:[1,0,1] neg_lo:[0,0,1] neg_hi:[0,0,1]
	v_cndmask_b32_e32 v131, v131, v143, vcc
	v_pk_fma_f32 v[60:61], v[60:61], v[0:1], v[56:57] op_sel_hi:[1,0,1] neg_lo:[0,0,1] neg_hi:[0,0,1]
	v_pk_fma_f32 v[62:63], v[62:63], v[0:1], v[58:59] op_sel_hi:[1,0,1] neg_lo:[0,0,1] neg_hi:[0,0,1]
	ds_read_b128 v[202:205], v124 offset:45584
	ds_read_b128 v[198:201], v124 offset:45568
	v_pk_fma_f32 v[36:37], v[36:37], v[48:49], v[64:65]
	v_pk_fma_f32 v[38:39], v[38:39], v[50:51], v[66:67]
	v_pk_fma_f32 v[32:33], v[32:33], v[40:41], v[60:61]
	v_pk_fma_f32 v[34:35], v[34:35], v[42:43], v[62:63]
	s_waitcnt lgkmcnt(2)
	v_pk_mul_f32 v[156:157], v[32:33], v[156:157]
	v_pk_mul_f32 v[52:53], v[32:33], v[52:53]
	v_pk_mul_f32 v[158:159], v[34:35], v[158:159]
	v_pk_mul_f32 v[54:55], v[34:35], v[54:55]
	v_pk_fma_f32 v[152:153], v[36:37], v[152:153], v[156:157]
	v_pk_fma_f32 v[44:45], v[36:37], v[44:45], v[52:53]
	v_pk_fma_f32 v[154:155], v[38:39], v[154:155], v[158:159]
	v_pk_fma_f32 v[46:47], v[38:39], v[46:47], v[54:55]
	v_pk_add_f32 v[152:153], v[152:153], v[154:155]
	v_pk_add_f32 v[44:45], v[44:45], v[46:47]
	v_add_f32_e32 v142, v152, v153
	v_add_f32_e32 v143, v44, v45
	ds_read_b128 v[76:79], v124 offset:46352
	v_add_f32_dpp v142, v142, v142 quad_perm:[1,0,3,2] row_mask:0xf bank_mask:0xf bound_ctrl:1
	v_add_f32_dpp v143, v143, v143 quad_perm:[1,0,3,2] row_mask:0xf bank_mask:0xf bound_ctrl:1
	ds_read_b128 v[72:75], v124 offset:46336
	v_add_f32_dpp v142, v142, v142 quad_perm:[2,3,0,1] row_mask:0xf bank_mask:0xf bound_ctrl:1
	v_add_f32_dpp v143, v143, v143 quad_perm:[2,3,0,1] row_mask:0xf bank_mask:0xf bound_ctrl:1
	ds_read_b128 v[68:71], v124 offset:46592
	v_add_f32_dpp v142, v142, v142 row_half_mirror row_mask:0xf bank_mask:0xf bound_ctrl:1
	v_add_f32_dpp v143, v143, v143 row_half_mirror row_mask:0xf bank_mask:0xf bound_ctrl:1
	ds_read_b128 v[56:59], v124 offset:46608
	ds_read_b32 v0, v135 offset:47360
	ds_read_b128 v[64:67], v124 offset:46848
	ds_read_b128 v[60:63], v124 offset:46864
	ds_read_b128 v[48:51], v124 offset:46080
	ds_read_b128 v[40:43], v124 offset:46096
	v_pk_mul_f32 v[182:183], v[182:183], v[142:143] op_sel_hi:[1,0]
	v_pk_mul_f32 v[184:185], v[184:185], v[142:143] op_sel_hi:[1,0]
	s_lshl_b64 vcc, vcc, 1
	v_pk_mul_f32 v[186:187], v[186:187], v[142:143] op_sel_hi:[1,0]
	v_pk_mul_f32 v[188:189], v[188:189], v[142:143] op_sel_hi:[1,0]
	v_pk_fma_f32 v[190:191], v[190:191], v[160:161], v[182:183] op_sel_hi:[1,0,1] neg_lo:[0,0,1] neg_hi:[0,0,1]
	v_pk_fma_f32 v[192:193], v[192:193], v[160:161], v[184:185] op_sel_hi:[1,0,1] neg_lo:[0,0,1] neg_hi:[0,0,1]
	v_cndmask_b32_e32 v131, v131, v143, vcc
	v_pk_fma_f32 v[194:195], v[194:195], v[160:161], v[186:187] op_sel_hi:[1,0,1] neg_lo:[0,0,1] neg_hi:[0,0,1]
	v_pk_fma_f32 v[196:197], v[196:197], v[160:161], v[188:189] op_sel_hi:[1,0,1] neg_lo:[0,0,1] neg_hi:[0,0,1]
	ds_read_b128 v[52:55], v124 offset:47120
	ds_read_b128 v[44:47], v124 offset:47104
	v_pk_fma_f32 v[36:37], v[36:37], v[144:145], v[190:191]
	v_pk_fma_f32 v[38:39], v[38:39], v[146:147], v[192:193]
	v_pk_fma_f32 v[32:33], v[32:33], v[148:149], v[194:195]
	v_pk_fma_f32 v[34:35], v[34:35], v[150:151], v[196:197]
	s_waitcnt lgkmcnt(2)
	v_pk_mul_f32 v[76:77], v[32:33], v[76:77]
	v_pk_mul_f32 v[202:203], v[32:33], v[202:203]
	v_pk_mul_f32 v[78:79], v[34:35], v[78:79]
	v_pk_mul_f32 v[204:205], v[34:35], v[204:205]
	v_pk_fma_f32 v[72:73], v[36:37], v[72:73], v[76:77]
	v_pk_fma_f32 v[198:199], v[36:37], v[198:199], v[202:203]
	v_pk_fma_f32 v[74:75], v[38:39], v[74:75], v[78:79]
	v_pk_fma_f32 v[200:201], v[38:39], v[200:201], v[204:205]
	v_pk_add_f32 v[72:73], v[72:73], v[74:75]
	v_pk_add_f32 v[198:199], v[198:199], v[200:201]
	v_add_f32_e32 v142, v72, v73
	v_add_f32_e32 v143, v198, v199
	ds_read_b128 v[156:159], v124 offset:47888
	v_add_f32_dpp v142, v142, v142 quad_perm:[1,0,3,2] row_mask:0xf bank_mask:0xf bound_ctrl:1
	v_add_f32_dpp v143, v143, v143 quad_perm:[1,0,3,2] row_mask:0xf bank_mask:0xf bound_ctrl:1
	ds_read_b128 v[152:155], v124 offset:47872
	v_add_f32_dpp v142, v142, v142 quad_perm:[2,3,0,1] row_mask:0xf bank_mask:0xf bound_ctrl:1
	v_add_f32_dpp v143, v143, v143 quad_perm:[2,3,0,1] row_mask:0xf bank_mask:0xf bound_ctrl:1
	ds_read_b128 v[182:185], v124 offset:48128
	v_add_f32_dpp v142, v142, v142 row_half_mirror row_mask:0xf bank_mask:0xf bound_ctrl:1
	v_add_f32_dpp v143, v143, v143 row_half_mirror row_mask:0xf bank_mask:0xf bound_ctrl:1
	ds_read_b128 v[186:189], v124 offset:48144
	ds_read_b32 v160, v135 offset:48896
	ds_read_b128 v[190:193], v124 offset:48384
	ds_read_b128 v[194:197], v124 offset:48400
	ds_read_b128 v[144:147], v124 offset:47616
	ds_read_b128 v[148:151], v124 offset:47632
	v_pk_mul_f32 v[68:69], v[68:69], v[142:143] op_sel_hi:[1,0]
	v_pk_mul_f32 v[70:71], v[70:71], v[142:143] op_sel_hi:[1,0]
	s_lshl_b64 vcc, vcc, 1
	v_pk_mul_f32 v[56:57], v[56:57], v[142:143] op_sel_hi:[1,0]
	v_pk_mul_f32 v[58:59], v[58:59], v[142:143] op_sel_hi:[1,0]
	v_pk_fma_f32 v[64:65], v[64:65], v[0:1], v[68:69] op_sel_hi:[1,0,1] neg_lo:[0,0,1] neg_hi:[0,0,1]
	v_pk_fma_f32 v[66:67], v[66:67], v[0:1], v[70:71] op_sel_hi:[1,0,1] neg_lo:[0,0,1] neg_hi:[0,0,1]
	v_cndmask_b32_e32 v131, v131, v143, vcc
	v_pk_fma_f32 v[60:61], v[60:61], v[0:1], v[56:57] op_sel_hi:[1,0,1] neg_lo:[0,0,1] neg_hi:[0,0,1]
	v_pk_fma_f32 v[62:63], v[62:63], v[0:1], v[58:59] op_sel_hi:[1,0,1] neg_lo:[0,0,1] neg_hi:[0,0,1]
	ds_read_b128 v[202:205], v124 offset:48656
	ds_read_b128 v[198:201], v124 offset:48640
	v_pk_fma_f32 v[36:37], v[36:37], v[48:49], v[64:65]
	v_pk_fma_f32 v[38:39], v[38:39], v[50:51], v[66:67]
	v_pk_fma_f32 v[32:33], v[32:33], v[40:41], v[60:61]
	v_pk_fma_f32 v[34:35], v[34:35], v[42:43], v[62:63]
	s_waitcnt lgkmcnt(2)
	v_pk_mul_f32 v[156:157], v[32:33], v[156:157]
	v_pk_mul_f32 v[52:53], v[32:33], v[52:53]
	v_pk_mul_f32 v[158:159], v[34:35], v[158:159]
	v_pk_mul_f32 v[54:55], v[34:35], v[54:55]
	v_pk_fma_f32 v[152:153], v[36:37], v[152:153], v[156:157]
	v_pk_fma_f32 v[44:45], v[36:37], v[44:45], v[52:53]
	v_pk_fma_f32 v[154:155], v[38:39], v[154:155], v[158:159]
	v_pk_fma_f32 v[46:47], v[38:39], v[46:47], v[54:55]
	v_pk_add_f32 v[152:153], v[152:153], v[154:155]
	v_pk_add_f32 v[44:45], v[44:45], v[46:47]
	v_add_f32_e32 v142, v152, v153
	v_add_f32_e32 v143, v44, v45
	s_nop 0
	v_add_f32_dpp v142, v142, v142 quad_perm:[1,0,3,2] row_mask:0xf bank_mask:0xf bound_ctrl:1
	v_add_f32_dpp v143, v143, v143 quad_perm:[1,0,3,2] row_mask:0xf bank_mask:0xf bound_ctrl:1
	s_nop 0
	v_add_f32_dpp v142, v142, v142 quad_perm:[2,3,0,1] row_mask:0xf bank_mask:0xf bound_ctrl:1
	v_add_f32_dpp v143, v143, v143 quad_perm:[2,3,0,1] row_mask:0xf bank_mask:0xf bound_ctrl:1
	s_nop 0
	v_add_f32_dpp v142, v142, v142 row_half_mirror row_mask:0xf bank_mask:0xf bound_ctrl:1
	v_add_f32_dpp v143, v143, v143 row_half_mirror row_mask:0xf bank_mask:0xf bound_ctrl:1
	v_pk_mul_f32 v[182:183], v[182:183], v[142:143] op_sel_hi:[1,0]
	v_pk_mul_f32 v[184:185], v[184:185], v[142:143] op_sel_hi:[1,0]
	s_lshl_b64 vcc, vcc, 1
	v_pk_mul_f32 v[186:187], v[186:187], v[142:143] op_sel_hi:[1,0]
	v_pk_mul_f32 v[188:189], v[188:189], v[142:143] op_sel_hi:[1,0]
	v_pk_fma_f32 v[190:191], v[190:191], v[160:161], v[182:183] op_sel_hi:[1,0,1] neg_lo:[0,0,1] neg_hi:[0,0,1]
	v_pk_fma_f32 v[192:193], v[192:193], v[160:161], v[184:185] op_sel_hi:[1,0,1] neg_lo:[0,0,1] neg_hi:[0,0,1]
	v_cndmask_b32_e32 v131, v131, v143, vcc
	v_pk_fma_f32 v[194:195], v[194:195], v[160:161], v[186:187] op_sel_hi:[1,0,1] neg_lo:[0,0,1] neg_hi:[0,0,1]
	v_pk_fma_f32 v[196:197], v[196:197], v[160:161], v[188:189] op_sel_hi:[1,0,1] neg_lo:[0,0,1] neg_hi:[0,0,1]
	v_pk_fma_f32 v[36:37], v[36:37], v[144:145], v[190:191]
	v_pk_fma_f32 v[38:39], v[38:39], v[146:147], v[192:193]
	v_pk_fma_f32 v[32:33], v[32:33], v[148:149], v[194:195]
	v_pk_fma_f32 v[34:35], v[34:35], v[150:151], v[196:197]
	s_waitcnt lgkmcnt(0)
	v_pk_mul_f32 v[202:203], v[32:33], v[202:203]
	v_pk_mul_f32 v[204:205], v[34:35], v[204:205]
	v_pk_fma_f32 v[198:199], v[36:37], v[198:199], v[202:203]
	v_pk_fma_f32 v[200:201], v[38:39], v[200:201], v[204:205]
	v_pk_add_f32 v[198:199], v[198:199], v[200:201]
	v_add_f32_e32 v143, v198, v199
	s_nop 1
	v_add_f32_dpp v143, v143, v143 quad_perm:[1,0,3,2] row_mask:0xf bank_mask:0xf bound_ctrl:1
	s_nop 1
	v_add_f32_dpp v143, v143, v143 quad_perm:[2,3,0,1] row_mask:0xf bank_mask:0xf bound_ctrl:1
	s_nop 1
	v_add_f32_dpp v143, v143, v143 row_half_mirror row_mask:0xf bank_mask:0xf bound_ctrl:1
	s_lshl_b64 vcc, vcc, 1
	v_cndmask_b32_e32 v131, v131, v143, vcc
	s_setprio 0
	s_lshl_b32 s70, s64, 5
	s_add_u32 s70, s70, s4
	v_add_u32_e32 v40, s70, v86
	v_lshlrev_b32_e32 v46, 1, v112
	v_mul_u32_u24_e32 v41, 0xc00, v40
	v_add_u32_e32 v41, v41, v46
	v_bfe_u32 v47, v134, 16, 1
	v_add3_u32 v47, v134, v47, s78
	global_store_short_d16_hi v41, v47, s[60:61]
	v_bfe_u32 v47, v133, 16, 1
	v_add3_u32 v47, v133, v47, s78
	v_add_u32_e32 v45, 0x6000, v41
	global_store_short_d16_hi v45, v47, s[60:61]
	v_bfe_u32 v47, v132, 16, 1
	v_add3_u32 v47, v132, v47, s78
	v_add_u32_e32 v45, 0xc000, v41
	global_store_short_d16_hi v45, v47, s[60:61]
	v_bfe_u32 v47, v131, 16, 1
	v_add3_u32 v47, v131, v47, s78
	v_add_u32_e32 v45, 0x12000, v41
	global_store_short_d16_hi v45, v47, s[60:61]
	s_mov_b64 s[20:21], 0
	s_branch .LBB0_654

.LBB0_654:
	s_add_i32 s64, s64, 1
	s_xor_b64 s[68:69], s[68:69], -1
	s_cmp_eq_u32 s64, s84
	s_waitcnt lgkmcnt(0)
	s_barrier
	s_cbranch_scc1 .LBB0_656
	s_and_b64 vcc, exec, s[36:37]
	s_cbranch_vccnz .Lrw_norm655
	s_and_b64 vcc, exec, s[76:77]
	s_cbranch_vccz .Lrw_norm655
	s_mov_b64 s[20:21], -1
	s_branch .Lrw_fast
.Lrw_norm655:
	v_mov_b64_e32 v[24:25], v[36:37]
	v_mov_b64_e32 v[28:29], v[32:33]
	v_mov_b64_e32 v[26:27], v[38:39]
	v_mov_b64_e32 v[30:31], v[34:35]
	s_and_b64 vcc, exec, s[76:77]
	s_mov_b64 s[20:21], -1
	s_cbranch_vccnz .LBB0_603
	s_branch .LBB0_632
